# gates buffer: per-lane bj=0/1 byte groups stored adjacently -> one dwordx4 store (in-proj epilogue) and one dwordx4 load (branch-out epilogue) instead of two dwordx2 each
# speedup vs baseline: 1.0168x; 1.0062x over previous
.LBB0_201:
	s_ashr_i32 s0, s23, 2
	s_lshl_b32 s4, s0, 10
	s_lshl_b32 s1, s23, 8
	s_and_b32 s1, s1, 0x300
	s_ashr_i32 s5, s4, 31
	s_cmp_lt_i32 s0, 2
	s_cselect_b64 s[2:3], -1, 0
	s_cmp_gt_i32 s0, 1
	v_or_b32_e32 v0, s1, v204
	s_cselect_b64 s[0:1], -1, 0
	s_add_u32 s4, s18, s4
	s_addc_u32 s5, s19, s5
	v_lshl_add_u32 v158, s42, 8, v202
	v_lshl_add_u64 v[170:171], s[4:5], 0, v[0:1]
	v_mov_b32_e32 v250, v204
	v_mov_b32_e32 v251, 0
	v_lshl_add_u64 v[170:171], v[170:171], 0, v[250:251]
	s_movk_i32 s4, 0xc00
	v_mad_i64_i32 v[142:143], s[4:5], v158, s4, v[170:171]
	global_load_dwordx4 v[190:193], v[142:143], off
	s_and_b64 vcc, exec, s[0:1]
	s_mov_b32 s24, 0x3f317217
	s_cbranch_vccnz .LBB0_203
	global_load_dwordx4 v[154:157], v[142:143], off offset:1024
.LBB0_203:
	v_cndmask_b32_e64 v144, 0, 1, s[2:3]
	v_cmp_ne_u32_e64 s[44:45], 1, v144
	s_andn2_b64 vcc, exec, s[2:3]
	s_cbranch_vccnz .LBB0_205
.LBB0_205:
	v_or_b32_e32 v188, 16, v158
	s_movk_i32 s2, 0xc00
	v_mad_i64_i32 v[142:143], s[2:3], v188, s2, v[170:171]
	global_load_dwordx4 v[184:187], v[142:143], off
	s_and_b64 vcc, exec, s[44:45]
	v_ashrrev_i32_e32 v159, 31, v158
	s_cbranch_vccnz .LBB0_207
	global_load_dwordx4 v[150:153], v[142:143], off offset:1024
.LBB0_207:
	s_and_b64 vcc, exec, s[44:45]
	s_cbranch_vccnz .LBB0_209
.LBB0_209:
	v_or_b32_e32 v182, 32, v158
	s_movk_i32 s2, 0xc00
	v_mad_i64_i32 v[142:143], s[2:3], v182, s2, v[170:171]
	global_load_dwordx4 v[178:181], v[142:143], off
	s_and_b64 vcc, exec, s[44:45]
	s_cbranch_vccnz .LBB0_211
	global_load_dwordx4 v[146:149], v[142:143], off offset:1024

.LBB0_213:
	v_or_b32_e32 v176, 48, v158
	s_movk_i32 s2, 0xc00
	v_mad_i64_i32 v[194:195], s[2:3], v176, s2, v[170:171]
	global_load_dwordx4 v[172:175], v[194:195], off
	s_and_b64 vcc, exec, s[44:45]
	s_cbranch_vccnz .LBB0_215
	global_load_dwordx4 v[142:145], v[194:195], off offset:1024

.LBB0_249:
	v_add_u32_e32 v190, 0x80, v158
	s_movk_i32 s0, 0xc00
	v_mad_i64_i32 v[172:173], s[0:1], v190, s0, v[170:171]
	global_load_dwordx4 v[186:189], v[172:173], off
	s_and_b64 vcc, exec, s[44:45]
	s_cbranch_vccnz .LBB0_251
	global_load_dwordx4 v[154:157], v[172:173], off offset:1024

.LBB0_253:
	v_add_u32_e32 v184, 0x90, v158
	s_movk_i32 s0, 0xc00
	v_mad_i64_i32 v[172:173], s[0:1], v184, s0, v[170:171]
	global_load_dwordx4 v[180:183], v[172:173], off
	s_and_b64 vcc, exec, s[44:45]
	s_cbranch_vccnz .LBB0_255
	global_load_dwordx4 v[150:153], v[172:173], off offset:1024

.LBB0_257:
	v_add_u32_e32 v178, 0xa0, v158
	s_movk_i32 s0, 0xc00
	v_mad_i64_i32 v[172:173], s[0:1], v178, s0, v[170:171]
	global_load_dwordx4 v[174:177], v[172:173], off
	s_and_b64 vcc, exec, s[44:45]
	s_cbranch_vccnz .LBB0_259
	global_load_dwordx4 v[146:149], v[172:173], off offset:1024

.LBB0_261:
	v_add_u32_e32 v172, 0xb0, v158
	s_movk_i32 s0, 0xc00
	v_mad_i64_i32 v[192:193], s[0:1], v172, s0, v[170:171]
	global_load_dwordx4 v[246:249], v[192:193], off
	s_and_b64 vcc, exec, s[44:45]
	s_cbranch_vccnz .LBB0_263
	global_load_dwordx4 v[142:145], v[192:193], off offset:1024

.LBB0_265:
	v_ashrrev_i32_e32 v191, 31, v190
	v_lshlrev_b64 v[198:199], 11, v[190:191]
	s_waitcnt vmcnt(0)
	v_mov_b32_e32 v158, v246
	v_mov_b32_e32 v159, v247
	v_mov_b32_e32 v170, v248
	v_mov_b32_e32 v171, v249
	v_cvt_f32_ubyte1_e32 v191, v188
	v_cvt_f32_ubyte0_e32 v190, v188
	v_cvt_f32_ubyte1_e32 v193, v189
	v_cvt_f32_ubyte0_e32 v192, v189
	v_cvt_f32_ubyte3_e32 v195, v188
	v_cvt_f32_ubyte2_e32 v194, v188
	v_cvt_f32_ubyte3_e32 v197, v189
	v_cvt_f32_ubyte2_e32 v196, v189
	v_pk_mul_f32 v[190:191], v[62:63], v[190:191]
	v_pk_mul_f32 v[192:193], v[58:59], v[192:193]
	v_pk_mul_f32 v[194:195], v[64:65], v[194:195]
	v_pk_mul_f32 v[196:197], v[60:61], v[196:197]
	s_mov_b64 s[0:1], -1
	s_and_b64 vcc, exec, s[42:43]
	v_lshl_add_u64 v[188:189], s[36:37], 0, v[198:199]
	s_cbranch_vccnz .LBB0_267
	s_mov_b32 s0, 0x3b808081
	v_pk_mul_f32 v[200:201], v[194:195], s[0:1] op_sel_hi:[1,0]
	v_pk_mul_f32 v[198:199], v[190:191], s[0:1] op_sel_hi:[1,0]
	v_pk_mul_f32 v[206:207], v[196:197], s[0:1] op_sel_hi:[1,0]
	v_pk_mul_f32 v[224:225], v[192:193], s[0:1] op_sel_hi:[1,0]
	v_cvt_pk_bf16_f32 v198, v198, v199
	v_cvt_pk_bf16_f32 v199, v200, v201
	v_cvt_pk_bf16_f32 v201, v206, v207
	v_lshl_add_u64 v[206:207], v[188:189], 0, v[0:1]
	s_mov_b64 s[0:1], 0
	v_cvt_pk_bf16_f32 v200, v224, v225
	global_store_dwordx4 v[206:207], v[198:201], off

.LBB0_269:
	v_cvt_f32_ubyte1_e32 v157, v186
	v_cvt_f32_ubyte0_e32 v156, v186
	v_cvt_f32_ubyte1_e32 v191, v187
	v_cvt_f32_ubyte0_e32 v190, v187
	v_cvt_f32_ubyte3_e32 v193, v186
	v_cvt_f32_ubyte2_e32 v192, v186
	v_cvt_f32_ubyte3_e32 v195, v187
	v_cvt_f32_ubyte2_e32 v194, v187
	v_pk_mul_f32 v[156:157], v[30:31], v[156:157]
	v_pk_mul_f32 v[190:191], v[26:27], v[190:191]
	v_pk_mul_f32 v[192:193], v[32:33], v[192:193]
	v_pk_mul_f32 v[186:187], v[28:29], v[194:195]
	s_and_b64 vcc, exec, s[42:43]
	s_mov_b64 s[0:1], -1
	s_cbranch_vccnz .LBB0_271
	s_mov_b32 s0, 0x3b808081
	v_pk_mul_f32 v[196:197], v[192:193], s[0:1] op_sel_hi:[1,0]
	v_pk_mul_f32 v[194:195], v[156:157], s[0:1] op_sel_hi:[1,0]
	v_pk_mul_f32 v[198:199], v[186:187], s[0:1] op_sel_hi:[1,0]
	v_pk_mul_f32 v[200:201], v[190:191], s[0:1] op_sel_hi:[1,0]
	v_lshl_add_u64 v[188:189], v[188:189], 0, v[0:1]
	s_mov_b64 s[0:1], 0
	v_cvt_pk_bf16_f32 v194, v194, v195
	v_cvt_pk_bf16_f32 v195, v196, v197
	v_cvt_pk_bf16_f32 v196, v200, v201
	v_cvt_pk_bf16_f32 v197, v198, v199
	global_store_dwordx4 v[188:189], v[194:197], off offset:256

.LBB0_273:
	v_ashrrev_i32_e32 v185, 31, v184
	v_lshlrev_b64 v[154:155], 11, v[184:185]
	v_cvt_f32_ubyte1_e32 v157, v182
	v_cvt_f32_ubyte0_e32 v156, v182
	v_cvt_f32_ubyte1_e32 v185, v183
	v_cvt_f32_ubyte0_e32 v184, v183
	v_cvt_f32_ubyte3_e32 v187, v182
	v_cvt_f32_ubyte2_e32 v186, v182
	v_cvt_f32_ubyte3_e32 v189, v183
	v_cvt_f32_ubyte2_e32 v188, v183
	v_pk_mul_f32 v[156:157], v[54:55], v[156:157]
	v_pk_mul_f32 v[184:185], v[50:51], v[184:185]
	v_pk_mul_f32 v[186:187], v[56:57], v[186:187]
	v_pk_mul_f32 v[182:183], v[52:53], v[188:189]
	s_mov_b64 s[0:1], -1
	s_and_b64 vcc, exec, s[42:43]
	v_lshl_add_u64 v[154:155], s[36:37], 0, v[154:155]
	s_cbranch_vccnz .LBB0_275
	s_mov_b32 s0, 0x3b808081
	v_pk_mul_f32 v[190:191], v[186:187], s[0:1] op_sel_hi:[1,0]
	v_pk_mul_f32 v[188:189], v[156:157], s[0:1] op_sel_hi:[1,0]
	v_pk_mul_f32 v[192:193], v[182:183], s[0:1] op_sel_hi:[1,0]
	v_pk_mul_f32 v[194:195], v[184:185], s[0:1] op_sel_hi:[1,0]
	v_cvt_pk_bf16_f32 v188, v188, v189
	v_cvt_pk_bf16_f32 v189, v190, v191
	v_cvt_pk_bf16_f32 v191, v192, v193
	v_lshl_add_u64 v[192:193], v[154:155], 0, v[0:1]
	s_mov_b64 s[0:1], 0
	v_cvt_pk_bf16_f32 v190, v194, v195
	global_store_dwordx4 v[192:193], v[188:191], off

.LBB0_277:
	v_cvt_f32_ubyte1_e32 v153, v180
	v_cvt_f32_ubyte0_e32 v152, v180
	v_cvt_f32_ubyte1_e32 v157, v181
	v_cvt_f32_ubyte0_e32 v156, v181
	v_cvt_f32_ubyte3_e32 v183, v180
	v_cvt_f32_ubyte2_e32 v182, v180
	v_cvt_f32_ubyte3_e32 v185, v181
	v_cvt_f32_ubyte2_e32 v184, v181
	v_pk_mul_f32 v[152:153], v[22:23], v[152:153]
	v_pk_mul_f32 v[156:157], v[18:19], v[156:157]
	v_pk_mul_f32 v[182:183], v[24:25], v[182:183]
	v_pk_mul_f32 v[180:181], v[20:21], v[184:185]
	s_and_b64 vcc, exec, s[42:43]
	s_mov_b64 s[0:1], -1
	s_cbranch_vccnz .LBB0_279
	s_mov_b32 s0, 0x3b808081
	v_pk_mul_f32 v[186:187], v[182:183], s[0:1] op_sel_hi:[1,0]
	v_pk_mul_f32 v[184:185], v[152:153], s[0:1] op_sel_hi:[1,0]
	v_pk_mul_f32 v[188:189], v[180:181], s[0:1] op_sel_hi:[1,0]
	v_pk_mul_f32 v[190:191], v[156:157], s[0:1] op_sel_hi:[1,0]
	v_lshl_add_u64 v[154:155], v[154:155], 0, v[0:1]
	s_mov_b64 s[0:1], 0
	v_cvt_pk_bf16_f32 v184, v184, v185
	v_cvt_pk_bf16_f32 v185, v186, v187
	v_cvt_pk_bf16_f32 v186, v190, v191
	v_cvt_pk_bf16_f32 v187, v188, v189
	global_store_dwordx4 v[154:155], v[184:187], off offset:256

.LBB0_281:
	v_ashrrev_i32_e32 v179, 31, v178
	v_lshlrev_b64 v[150:151], 11, v[178:179]
	v_cvt_f32_ubyte1_e32 v153, v176
	v_cvt_f32_ubyte0_e32 v152, v176
	v_cvt_f32_ubyte1_e32 v155, v177
	v_cvt_f32_ubyte0_e32 v154, v177
	v_cvt_f32_ubyte3_e32 v157, v176
	v_cvt_f32_ubyte2_e32 v156, v176
	v_cvt_f32_ubyte3_e32 v179, v177
	v_cvt_f32_ubyte2_e32 v178, v177
	v_pk_mul_f32 v[152:153], v[46:47], v[152:153]
	v_pk_mul_f32 v[154:155], v[42:43], v[154:155]
	v_pk_mul_f32 v[156:157], v[48:49], v[156:157]
	v_pk_mul_f32 v[176:177], v[44:45], v[178:179]
	s_mov_b64 s[0:1], -1
	s_and_b64 vcc, exec, s[42:43]
	v_lshl_add_u64 v[150:151], s[36:37], 0, v[150:151]
	s_cbranch_vccnz .LBB0_283
	s_mov_b32 s0, 0x3b808081
	v_pk_mul_f32 v[180:181], v[156:157], s[0:1] op_sel_hi:[1,0]
	v_pk_mul_f32 v[178:179], v[152:153], s[0:1] op_sel_hi:[1,0]
	v_pk_mul_f32 v[182:183], v[176:177], s[0:1] op_sel_hi:[1,0]
	v_pk_mul_f32 v[184:185], v[154:155], s[0:1] op_sel_hi:[1,0]
	v_cvt_pk_bf16_f32 v178, v178, v179
	v_cvt_pk_bf16_f32 v179, v180, v181
	v_cvt_pk_bf16_f32 v181, v182, v183
	v_lshl_add_u64 v[182:183], v[150:151], 0, v[0:1]
	s_mov_b64 s[0:1], 0
	v_cvt_pk_bf16_f32 v180, v184, v185
	global_store_dwordx4 v[182:183], v[178:181], off

.LBB0_285:
	v_cvt_f32_ubyte1_e32 v149, v174
	v_cvt_f32_ubyte0_e32 v148, v174
	v_cvt_f32_ubyte1_e32 v153, v175
	v_cvt_f32_ubyte0_e32 v152, v175
	v_cvt_f32_ubyte3_e32 v155, v174
	v_cvt_f32_ubyte2_e32 v154, v174
	v_cvt_f32_ubyte3_e32 v157, v175
	v_cvt_f32_ubyte2_e32 v156, v175
	v_pk_mul_f32 v[148:149], v[14:15], v[148:149]
	v_pk_mul_f32 v[152:153], v[10:11], v[152:153]
	v_pk_mul_f32 v[154:155], v[16:17], v[154:155]
	v_pk_mul_f32 v[156:157], v[12:13], v[156:157]
	s_and_b64 vcc, exec, s[42:43]
	s_mov_b64 s[0:1], -1
	s_cbranch_vccnz .LBB0_287
	s_mov_b32 s0, 0x3b808081
	v_pk_mul_f32 v[176:177], v[154:155], s[0:1] op_sel_hi:[1,0]
	v_pk_mul_f32 v[174:175], v[148:149], s[0:1] op_sel_hi:[1,0]
	v_pk_mul_f32 v[178:179], v[156:157], s[0:1] op_sel_hi:[1,0]
	v_pk_mul_f32 v[180:181], v[152:153], s[0:1] op_sel_hi:[1,0]
	v_lshl_add_u64 v[150:151], v[150:151], 0, v[0:1]
	s_mov_b64 s[0:1], 0
	v_cvt_pk_bf16_f32 v174, v174, v175
	v_cvt_pk_bf16_f32 v175, v176, v177
	v_cvt_pk_bf16_f32 v176, v180, v181
	v_cvt_pk_bf16_f32 v177, v178, v179
	global_store_dwordx4 v[150:151], v[174:177], off offset:256

.LBB0_289:
	v_ashrrev_i32_e32 v173, 31, v172
	v_lshlrev_b64 v[146:147], 11, v[172:173]
	v_cvt_f32_ubyte1_e32 v149, v170
	v_cvt_f32_ubyte0_e32 v148, v170
	v_cvt_f32_ubyte1_e32 v151, v171
	v_cvt_f32_ubyte0_e32 v150, v171
	v_cvt_f32_ubyte3_e32 v153, v170
	v_cvt_f32_ubyte2_e32 v152, v170
	v_cvt_f32_ubyte3_e32 v155, v171
	v_cvt_f32_ubyte2_e32 v154, v171
	v_pk_mul_f32 v[148:149], v[38:39], v[148:149]
	v_pk_mul_f32 v[150:151], v[34:35], v[150:151]
	v_pk_mul_f32 v[152:153], v[40:41], v[152:153]
	v_pk_mul_f32 v[154:155], v[36:37], v[154:155]
	s_mov_b64 s[0:1], -1
	s_and_b64 vcc, exec, s[42:43]
	v_lshl_add_u64 v[146:147], s[36:37], 0, v[146:147]
	s_cbranch_vccnz .LBB0_291
	s_mov_b32 s0, 0x3b808081
	v_pk_mul_f32 v[156:157], v[152:153], s[0:1] op_sel_hi:[1,0]
	v_pk_mul_f32 v[170:171], v[148:149], s[0:1] op_sel_hi:[1,0]
	v_pk_mul_f32 v[174:175], v[154:155], s[0:1] op_sel_hi:[1,0]
	v_pk_mul_f32 v[172:173], v[150:151], s[0:1] op_sel_hi:[1,0]
	v_cvt_pk_bf16_f32 v170, v170, v171
	v_cvt_pk_bf16_f32 v171, v156, v157
	v_lshl_add_u64 v[156:157], v[146:147], 0, v[0:1]
	s_mov_b64 s[0:1], 0
	v_cvt_pk_bf16_f32 v172, v172, v173
	v_cvt_pk_bf16_f32 v173, v174, v175
	global_store_dwordx4 v[156:157], v[170:173], off

.LBB0_293:
	v_cvt_f32_ubyte1_e32 v145, v158
	v_cvt_f32_ubyte0_e32 v144, v158
	v_cvt_f32_ubyte1_e32 v149, v159
	v_cvt_f32_ubyte0_e32 v148, v159
	v_cvt_f32_ubyte3_e32 v151, v158
	v_cvt_f32_ubyte2_e32 v150, v158
	v_cvt_f32_ubyte3_e32 v153, v159
	v_cvt_f32_ubyte2_e32 v152, v159
	v_pk_mul_f32 v[144:145], v[6:7], v[144:145]
	v_pk_mul_f32 v[148:149], v[2:3], v[148:149]
	v_pk_mul_f32 v[150:151], v[8:9], v[150:151]
	v_pk_mul_f32 v[152:153], v[4:5], v[152:153]
	s_and_b64 vcc, exec, s[42:43]
	s_mov_b64 s[0:1], -1
	s_cbranch_vccnz .LBB0_296
	s_mov_b32 s0, 0x3b808081
	v_pk_mul_f32 v[156:157], v[150:151], s[0:1] op_sel_hi:[1,0]
	v_pk_mul_f32 v[154:155], v[144:145], s[0:1] op_sel_hi:[1,0]
	v_pk_mul_f32 v[158:159], v[152:153], s[0:1] op_sel_hi:[1,0]
	v_pk_mul_f32 v[170:171], v[148:149], s[0:1] op_sel_hi:[1,0]
	v_lshl_add_u64 v[146:147], v[146:147], 0, v[0:1]
	v_cvt_pk_bf16_f32 v154, v154, v155
	v_cvt_pk_bf16_f32 v155, v156, v157
	v_cvt_pk_bf16_f32 v156, v170, v171
	v_cvt_pk_bf16_f32 v157, v158, v159
	global_store_dwordx4 v[146:147], v[154:157], off offset:256
	s_cbranch_execz .LBB0_297

.LBB0_701:
	v_lshl_add_u32 v142, s54, 8, v174
	v_ashrrev_i32_e32 v143, 31, v142
	v_lshl_add_u64 v[140:141], v[142:143], 3, s[2:3]
	global_load_dwordx2 v[158:159], v[140:141], off
	global_load_dwordx2 v[156:157], v[140:141], off offset:128
	global_load_dwordx2 v[154:155], v[140:141], off offset:256
	global_load_dwordx2 v[152:153], v[140:141], off offset:384
	global_load_dwordx2 v[150:151], v[140:141], off offset:1024
	global_load_dwordx2 v[148:149], v[140:141], off offset:1152
	global_load_dwordx2 v[146:147], v[140:141], off offset:1280
	global_load_dwordx2 v[144:145], v[140:141], off offset:1408
	s_cmp_gt_i32 s42, 13
	s_cselect_b64 s[0:1], -1, 0
	s_cmp_lt_i32 s42, 14
	s_cselect_b64 s[6:7], -1, 0
	s_and_b64 vcc, s[6:7], exec
	s_cselect_b32 s6, 0, -14
	s_movk_i32 s7, 0xe00
	s_mov_b32 s34, 0x800000
	s_cselect_b32 s25, s18, s31
	s_cselect_b32 s28, s17, s30
	s_cselect_b32 s24, s7, 0xc00
	s_add_i32 s6, s6, s42
	v_lshl_or_b32 v140, s6, 8, v176
	v_ashrrev_i32_e32 v141, 31, v140
	s_mov_b64 s[6:7], -1
	s_waitcnt vmcnt(0)
	v_ffbh_u32_e32 v143, v159
	v_min_u32_e32 v143, 32, v143
	v_lshlrev_b64 v[158:159], v143, v[158:159]
	v_min_u32_e32 v158, 1, v158
	v_or_b32_e32 v158, v159, v158
	v_cvt_f32_u32_e32 v158, v158
	v_sub_u32_e32 v143, 32, v143
	v_ldexp_f32 v143, v158, v143
	v_mul_f32_e32 v143, 0x33800000, v143
	v_fmamk_f32 v143, v143, 0x3a800000, v210
	v_cmp_gt_f32_e64 s[42:43], s34, v143
	v_mul_f32_e32 v158, 0x4b800000, v143
	s_nop 0
	v_cndmask_b32_e64 v143, v143, v158, s[42:43]
	v_rsq_f32_e32 v143, v143
	s_nop 0
	v_mul_f32_e32 v158, 0x45800000, v143
	v_cndmask_b32_e64 v158, v143, v158, s[42:43]
	v_pk_mul_f32 v[128:129], v[128:129], v[158:159] op_sel_hi:[1,0]
	v_pk_mul_f32 v[170:171], v[126:127], v[158:159] op_sel_hi:[1,0]
	v_pk_mul_f32 v[124:125], v[124:125], v[158:159] op_sel_hi:[1,0]
	v_pk_mul_f32 v[126:127], v[122:123], v[158:159] op_sel_hi:[1,0]
	s_cbranch_vccnz .LBB0_703
	v_mul_f32_e32 v122, 0xbfb8aa3b, v170
	v_exp_f32_e32 v122, v122
	v_mul_f32_e32 v143, 0xbfb8aa3b, v171
	v_exp_f32_e32 v143, v143
	v_mul_f32_e32 v123, 0xbfb8aa3b, v126
	v_exp_f32_e32 v123, v123
	v_mul_f32_e32 v159, 0xbfb8aa3b, v127
	v_add_f32_e32 v122, 1.0, v122
	v_exp_f32_e32 v159, v159
	v_rcp_f32_e32 v122, v122
	v_add_f32_e32 v143, 1.0, v143
	v_rcp_f32_e32 v143, v143
	v_add_f32_e32 v123, 1.0, v123
	v_rcp_f32_e32 v123, v123
	v_add_f32_e32 v159, 1.0, v159
	v_mul_f32_e32 v122, 0x437f0000, v122
	v_rcp_f32_e32 v159, v159
	v_max_f32_e32 v122, 1.0, v122
	v_mul_f32_e32 v143, 0x437f0000, v143
	v_rndne_f32_e32 v122, v122
	v_max_f32_e32 v143, 1.0, v143
	v_cvt_pk_u8_f32 v122, v122, 0, 0
	v_mul_f32_e32 v123, 0x437f0000, v123
	v_rndne_f32_e32 v143, v143
	v_max_f32_e32 v123, 1.0, v123
	v_cvt_pk_u8_f32 v122, v143, 1, v122
	v_mul_f32_e32 v143, 0xbfb8aa3b, v128
	v_mul_f32_e32 v159, 0x437f0000, v159
	v_rndne_f32_e32 v123, v123
	v_exp_f32_e32 v143, v143
	v_max_f32_e32 v159, 1.0, v159
	v_cvt_pk_u8_f32 v123, v123, 0, 0
	v_rndne_f32_e32 v159, v159
	v_cvt_pk_u8_f32 v123, v159, 1, v123
	v_mul_f32_e32 v159, 0xbfb8aa3b, v124
	v_exp_f32_e32 v159, v159
	v_add_f32_e32 v143, 1.0, v143
	v_rcp_f32_e32 v143, v143
	v_mul_f32_e32 v172, 0xbfb8aa3b, v129
	v_add_f32_e32 v159, 1.0, v159
	v_rcp_f32_e32 v159, v159
	v_exp_f32_e32 v172, v172
	v_mul_f32_e32 v143, 0x437f0000, v143
	v_max_f32_e32 v143, 1.0, v143
	v_rndne_f32_e32 v143, v143
	v_cvt_pk_u8_f32 v122, v143, 2, v122
	v_mul_f32_e32 v143, 0x437f0000, v159
	v_add_f32_e32 v159, 1.0, v172
	v_mul_f32_e32 v172, 0xbfb8aa3b, v125
	v_rcp_f32_e32 v159, v159
	v_exp_f32_e32 v172, v172
	v_max_f32_e32 v143, 1.0, v143
	v_rndne_f32_e32 v143, v143
	v_cvt_pk_u8_f32 v123, v143, 2, v123
	v_mul_f32_e32 v143, 0x437f0000, v159
	v_add_f32_e32 v159, 1.0, v172
	v_rcp_f32_e32 v159, v159
	v_max_f32_e32 v143, 1.0, v143
	v_rndne_f32_e32 v143, v143
	v_cvt_pk_u8_f32 v122, v143, 3, v122
	v_mul_f32_e32 v143, 0x437f0000, v159
	v_max_f32_e32 v143, 1.0, v143
	v_mov_b64_e32 v[172:173], s[30:31]
	v_rndne_f32_e32 v143, v143
	v_mad_i64_i32 v[172:173], s[6:7], v142, s55, v[172:173]
	v_cvt_pk_u8_f32 v123, v143, 3, v123
	v_lshl_add_u64 v[172:173], v[172:173], 0, v[140:141]
	s_mov_b64 s[6:7], 0
	v_mov_b32_e32 v246, v122
	v_mov_b32_e32 v247, v123

.LBB0_705:
	v_mov_b32_e32 v124, v158
	v_mov_b32_e32 v125, v158
	v_mov_b32_e32 v159, v158
	v_pk_mul_f32 v[120:121], v[120:121], v[124:125]
	v_pk_mul_f32 v[116:117], v[116:117], v[124:125]
	v_cndmask_b32_e64 v124, 0, 1, s[0:1]
	v_pk_mul_f32 v[118:119], v[118:119], v[158:159]
	v_pk_mul_f32 v[114:115], v[114:115], v[158:159]
	v_cmp_ne_u32_e64 s[42:43], 1, v124
	s_andn2_b64 vcc, exec, s[0:1]
	s_mov_b64 s[0:1], -1
	s_cbranch_vccnz .LBB0_707
	v_mul_f32_e32 v124, 0xbfb8aa3b, v118
	v_exp_f32_e32 v124, v124
	v_mul_f32_e32 v126, 0xbfb8aa3b, v119
	v_exp_f32_e32 v126, v126
	v_mul_f32_e32 v125, 0xbfb8aa3b, v114
	v_exp_f32_e32 v125, v125
	v_mul_f32_e32 v127, 0xbfb8aa3b, v115
	v_add_f32_e32 v124, 1.0, v124
	v_exp_f32_e32 v127, v127
	v_rcp_f32_e32 v124, v124
	v_add_f32_e32 v126, 1.0, v126
	v_rcp_f32_e32 v126, v126
	v_add_f32_e32 v125, 1.0, v125
	v_rcp_f32_e32 v125, v125
	v_add_f32_e32 v127, 1.0, v127
	v_mul_f32_e32 v124, 0x437f0000, v124
	v_rcp_f32_e32 v127, v127
	v_max_f32_e32 v124, 1.0, v124
	v_mul_f32_e32 v126, 0x437f0000, v126
	v_rndne_f32_e32 v124, v124
	v_max_f32_e32 v126, 1.0, v126
	v_cvt_pk_u8_f32 v124, v124, 0, 0
	v_mul_f32_e32 v125, 0x437f0000, v125
	v_rndne_f32_e32 v126, v126
	v_max_f32_e32 v125, 1.0, v125
	v_cvt_pk_u8_f32 v124, v126, 1, v124
	v_mul_f32_e32 v126, 0xbfb8aa3b, v120
	v_mul_f32_e32 v127, 0x437f0000, v127
	v_rndne_f32_e32 v125, v125
	v_exp_f32_e32 v126, v126
	v_max_f32_e32 v127, 1.0, v127
	v_cvt_pk_u8_f32 v125, v125, 0, 0
	v_rndne_f32_e32 v127, v127
	v_cvt_pk_u8_f32 v125, v127, 1, v125
	v_mul_f32_e32 v127, 0xbfb8aa3b, v116
	v_exp_f32_e32 v127, v127
	v_add_f32_e32 v126, 1.0, v126
	v_rcp_f32_e32 v126, v126
	v_mul_f32_e32 v128, 0xbfb8aa3b, v121
	v_add_f32_e32 v127, 1.0, v127
	v_rcp_f32_e32 v127, v127
	v_exp_f32_e32 v128, v128
	v_mul_f32_e32 v126, 0x437f0000, v126
	v_max_f32_e32 v126, 1.0, v126
	v_rndne_f32_e32 v126, v126
	v_cvt_pk_u8_f32 v124, v126, 2, v124
	v_mul_f32_e32 v126, 0x437f0000, v127
	v_add_f32_e32 v127, 1.0, v128
	v_mul_f32_e32 v128, 0xbfb8aa3b, v117
	v_rcp_f32_e32 v127, v127
	v_exp_f32_e32 v128, v128
	v_max_f32_e32 v126, 1.0, v126
	v_rndne_f32_e32 v126, v126
	v_cvt_pk_u8_f32 v125, v126, 2, v125
	v_mul_f32_e32 v126, 0x437f0000, v127
	v_add_f32_e32 v127, 1.0, v128
	v_rcp_f32_e32 v127, v127
	v_max_f32_e32 v126, 1.0, v126
	v_rndne_f32_e32 v126, v126
	v_cvt_pk_u8_f32 v124, v126, 3, v124
	v_mul_f32_e32 v126, 0x437f0000, v127
	v_max_f32_e32 v126, 1.0, v126
	v_rndne_f32_e32 v126, v126
	v_cvt_pk_u8_f32 v125, v126, 3, v125
	v_mov_b64_e32 v[126:127], s[30:31]
	v_mad_i64_i32 v[126:127], s[0:1], v142, s55, v[126:127]
	v_lshl_add_u64 v[126:127], v[126:127], 0, v[140:141]
	s_mov_b64 s[0:1], 0
	v_mov_b32_e32 v244, v124
	v_mov_b32_e32 v245, v125
	v_mov_b32_e32 v250, v176
	v_mov_b32_e32 v251, 0
	v_lshl_add_u64 v[126:127], v[126:127], 0, v[250:251]
	global_store_dwordx4 v[126:127], v[244:247], off

.LBB0_709:
	v_ffbh_u32_e32 v114, v157
	v_min_u32_e32 v116, 32, v114
	v_lshlrev_b64 v[114:115], v116, v[156:157]
	v_min_u32_e32 v114, 1, v114
	v_or_b32_e32 v114, v115, v114
	v_cvt_f32_u32_e32 v114, v114
	v_sub_u32_e32 v115, 32, v116
	v_or_b32_e32 v118, 16, v142
	s_mov_b64 s[0:1], -1
	v_ldexp_f32 v114, v114, v115
	v_mul_f32_e32 v114, 0x33800000, v114
	v_fmamk_f32 v114, v114, 0x3a800000, v210
	v_mul_f32_e32 v115, 0x4b800000, v114
	v_cmp_gt_f32_e32 vcc, s34, v114
	s_nop 1
	v_cndmask_b32_e32 v114, v114, v115, vcc
	v_rsq_f32_e32 v114, v114
	s_nop 0
	v_mul_f32_e32 v115, 0x45800000, v114
	v_cndmask_b32_e32 v114, v114, v115, vcc
	v_pk_mul_f32 v[112:113], v[112:113], v[114:115] op_sel_hi:[1,0]
	v_pk_mul_f32 v[116:117], v[110:111], v[114:115] op_sel_hi:[1,0]
	v_pk_mul_f32 v[108:109], v[108:109], v[114:115] op_sel_hi:[1,0]
	v_pk_mul_f32 v[110:111], v[106:107], v[114:115] op_sel_hi:[1,0]
	s_and_b64 vcc, exec, s[42:43]
	s_cbranch_vccnz .LBB0_711
	v_mul_f32_e32 v106, 0xbfb8aa3b, v116
	v_exp_f32_e32 v106, v106
	v_mul_f32_e32 v115, 0xbfb8aa3b, v117
	v_exp_f32_e32 v115, v115
	v_mul_f32_e32 v107, 0xbfb8aa3b, v110
	v_exp_f32_e32 v107, v107
	v_mul_f32_e32 v119, 0xbfb8aa3b, v111
	v_add_f32_e32 v106, 1.0, v106
	v_exp_f32_e32 v119, v119
	v_rcp_f32_e32 v106, v106
	v_add_f32_e32 v115, 1.0, v115
	v_rcp_f32_e32 v115, v115
	v_add_f32_e32 v107, 1.0, v107
	v_rcp_f32_e32 v107, v107
	v_add_f32_e32 v119, 1.0, v119
	v_mul_f32_e32 v106, 0x437f0000, v106
	v_rcp_f32_e32 v119, v119
	v_max_f32_e32 v106, 1.0, v106
	v_mul_f32_e32 v115, 0x437f0000, v115
	v_rndne_f32_e32 v106, v106
	v_max_f32_e32 v115, 1.0, v115
	v_cvt_pk_u8_f32 v106, v106, 0, 0
	v_mul_f32_e32 v107, 0x437f0000, v107
	v_rndne_f32_e32 v115, v115
	v_max_f32_e32 v107, 1.0, v107
	v_cvt_pk_u8_f32 v106, v115, 1, v106
	v_mul_f32_e32 v115, 0xbfb8aa3b, v112
	v_mul_f32_e32 v119, 0x437f0000, v119
	v_rndne_f32_e32 v107, v107
	v_exp_f32_e32 v115, v115
	v_max_f32_e32 v119, 1.0, v119
	v_cvt_pk_u8_f32 v107, v107, 0, 0
	v_rndne_f32_e32 v119, v119
	v_cvt_pk_u8_f32 v107, v119, 1, v107
	v_mul_f32_e32 v119, 0xbfb8aa3b, v108
	v_exp_f32_e32 v119, v119
	v_add_f32_e32 v115, 1.0, v115
	v_rcp_f32_e32 v115, v115
	v_mul_f32_e32 v120, 0xbfb8aa3b, v113
	v_add_f32_e32 v119, 1.0, v119
	v_rcp_f32_e32 v119, v119
	v_exp_f32_e32 v120, v120
	v_mul_f32_e32 v115, 0x437f0000, v115
	v_max_f32_e32 v115, 1.0, v115
	v_rndne_f32_e32 v115, v115
	v_cvt_pk_u8_f32 v106, v115, 2, v106
	v_mul_f32_e32 v115, 0x437f0000, v119
	v_add_f32_e32 v119, 1.0, v120
	v_mul_f32_e32 v120, 0xbfb8aa3b, v109
	v_rcp_f32_e32 v119, v119
	v_exp_f32_e32 v120, v120
	v_max_f32_e32 v115, 1.0, v115
	v_rndne_f32_e32 v115, v115
	v_cvt_pk_u8_f32 v107, v115, 2, v107
	v_mul_f32_e32 v115, 0x437f0000, v119
	v_add_f32_e32 v119, 1.0, v120
	v_rcp_f32_e32 v119, v119
	v_max_f32_e32 v115, 1.0, v115
	v_rndne_f32_e32 v115, v115
	v_cvt_pk_u8_f32 v106, v115, 3, v106
	v_mul_f32_e32 v115, 0x437f0000, v119
	v_max_f32_e32 v115, 1.0, v115
	v_mov_b64_e32 v[120:121], s[30:31]
	v_rndne_f32_e32 v115, v115
	v_mad_i64_i32 v[120:121], s[0:1], v118, s55, v[120:121]
	v_cvt_pk_u8_f32 v107, v115, 3, v107
	v_lshl_add_u64 v[120:121], v[120:121], 0, v[140:141]
	s_mov_b64 s[0:1], 0
	v_mov_b32_e32 v246, v106
	v_mov_b32_e32 v247, v107

.LBB0_713:
	v_mov_b32_e32 v115, v114
	v_mov_b32_e32 v108, v114
	v_mov_b32_e32 v109, v114
	v_pk_mul_f32 v[104:105], v[104:105], v[108:109]
	v_pk_mul_f32 v[102:103], v[102:103], v[114:115]
	v_pk_mul_f32 v[100:101], v[100:101], v[108:109]
	v_pk_mul_f32 v[98:99], v[98:99], v[114:115]
	s_and_b64 vcc, exec, s[42:43]
	s_mov_b64 s[0:1], -1
	s_cbranch_vccnz .LBB0_715
	v_mul_f32_e32 v108, 0xbfb8aa3b, v102
	v_exp_f32_e32 v108, v108
	v_mul_f32_e32 v110, 0xbfb8aa3b, v103
	v_exp_f32_e32 v110, v110
	v_mul_f32_e32 v109, 0xbfb8aa3b, v98
	v_exp_f32_e32 v109, v109
	v_mul_f32_e32 v111, 0xbfb8aa3b, v99
	v_add_f32_e32 v108, 1.0, v108
	v_exp_f32_e32 v111, v111
	v_rcp_f32_e32 v108, v108
	v_add_f32_e32 v110, 1.0, v110
	v_rcp_f32_e32 v110, v110
	v_add_f32_e32 v109, 1.0, v109
	v_rcp_f32_e32 v109, v109
	v_add_f32_e32 v111, 1.0, v111
	v_mul_f32_e32 v108, 0x437f0000, v108
	v_rcp_f32_e32 v111, v111
	v_max_f32_e32 v108, 1.0, v108
	v_mul_f32_e32 v110, 0x437f0000, v110
	v_rndne_f32_e32 v108, v108
	v_max_f32_e32 v110, 1.0, v110
	v_cvt_pk_u8_f32 v108, v108, 0, 0
	v_mul_f32_e32 v109, 0x437f0000, v109
	v_rndne_f32_e32 v110, v110
	v_max_f32_e32 v109, 1.0, v109
	v_cvt_pk_u8_f32 v108, v110, 1, v108
	v_mul_f32_e32 v110, 0xbfb8aa3b, v104
	v_mul_f32_e32 v111, 0x437f0000, v111
	v_rndne_f32_e32 v109, v109
	v_exp_f32_e32 v110, v110
	v_max_f32_e32 v111, 1.0, v111
	v_cvt_pk_u8_f32 v109, v109, 0, 0
	v_rndne_f32_e32 v111, v111
	v_cvt_pk_u8_f32 v109, v111, 1, v109
	v_mul_f32_e32 v111, 0xbfb8aa3b, v100
	v_exp_f32_e32 v111, v111
	v_add_f32_e32 v110, 1.0, v110
	v_rcp_f32_e32 v110, v110
	v_mul_f32_e32 v112, 0xbfb8aa3b, v105
	v_add_f32_e32 v111, 1.0, v111
	v_rcp_f32_e32 v111, v111
	v_exp_f32_e32 v112, v112
	v_mul_f32_e32 v110, 0x437f0000, v110
	v_max_f32_e32 v110, 1.0, v110
	v_rndne_f32_e32 v110, v110
	v_cvt_pk_u8_f32 v108, v110, 2, v108
	v_mul_f32_e32 v110, 0x437f0000, v111
	v_add_f32_e32 v111, 1.0, v112
	v_mul_f32_e32 v112, 0xbfb8aa3b, v101
	v_rcp_f32_e32 v111, v111
	v_exp_f32_e32 v112, v112
	v_max_f32_e32 v110, 1.0, v110
	v_rndne_f32_e32 v110, v110
	v_cvt_pk_u8_f32 v109, v110, 2, v109
	v_mul_f32_e32 v110, 0x437f0000, v111
	v_add_f32_e32 v111, 1.0, v112
	v_rcp_f32_e32 v111, v111
	v_max_f32_e32 v110, 1.0, v110
	v_rndne_f32_e32 v110, v110
	v_cvt_pk_u8_f32 v108, v110, 3, v108
	v_mul_f32_e32 v110, 0x437f0000, v111
	v_max_f32_e32 v110, 1.0, v110
	v_rndne_f32_e32 v110, v110
	v_cvt_pk_u8_f32 v109, v110, 3, v109
	v_mov_b64_e32 v[110:111], s[30:31]
	v_mad_i64_i32 v[110:111], s[0:1], v118, s55, v[110:111]
	v_lshl_add_u64 v[110:111], v[110:111], 0, v[140:141]
	s_mov_b64 s[0:1], 0
	v_mov_b32_e32 v244, v108
	v_mov_b32_e32 v245, v109
	v_mov_b32_e32 v250, v176
	v_mov_b32_e32 v251, 0
	v_lshl_add_u64 v[110:111], v[110:111], 0, v[250:251]
	global_store_dwordx4 v[110:111], v[244:247], off

.LBB0_717:
	v_ffbh_u32_e32 v98, v155
	v_min_u32_e32 v100, 32, v98
	v_lshlrev_b64 v[98:99], v100, v[154:155]
	v_min_u32_e32 v98, 1, v98
	v_or_b32_e32 v98, v99, v98
	v_cvt_f32_u32_e32 v98, v98
	v_sub_u32_e32 v99, 32, v100
	v_or_b32_e32 v102, 32, v142
	s_mov_b64 s[0:1], -1
	v_ldexp_f32 v98, v98, v99
	v_mul_f32_e32 v98, 0x33800000, v98
	v_fmamk_f32 v98, v98, 0x3a800000, v210
	v_mul_f32_e32 v99, 0x4b800000, v98
	v_cmp_gt_f32_e32 vcc, s34, v98
	s_nop 1
	v_cndmask_b32_e32 v98, v98, v99, vcc
	v_rsq_f32_e32 v98, v98
	s_nop 0
	v_mul_f32_e32 v99, 0x45800000, v98
	v_cndmask_b32_e32 v98, v98, v99, vcc
	v_pk_mul_f32 v[96:97], v[96:97], v[98:99] op_sel_hi:[1,0]
	v_pk_mul_f32 v[100:101], v[94:95], v[98:99] op_sel_hi:[1,0]
	v_pk_mul_f32 v[92:93], v[92:93], v[98:99] op_sel_hi:[1,0]
	v_pk_mul_f32 v[94:95], v[90:91], v[98:99] op_sel_hi:[1,0]
	s_and_b64 vcc, exec, s[42:43]
	s_cbranch_vccnz .LBB0_719
	v_mul_f32_e32 v90, 0xbfb8aa3b, v100
	v_exp_f32_e32 v90, v90
	v_mul_f32_e32 v99, 0xbfb8aa3b, v101
	v_exp_f32_e32 v99, v99
	v_mul_f32_e32 v91, 0xbfb8aa3b, v94
	v_exp_f32_e32 v91, v91
	v_mul_f32_e32 v103, 0xbfb8aa3b, v95
	v_add_f32_e32 v90, 1.0, v90
	v_exp_f32_e32 v103, v103
	v_rcp_f32_e32 v90, v90
	v_add_f32_e32 v99, 1.0, v99
	v_rcp_f32_e32 v99, v99
	v_add_f32_e32 v91, 1.0, v91
	v_rcp_f32_e32 v91, v91
	v_add_f32_e32 v103, 1.0, v103
	v_mul_f32_e32 v90, 0x437f0000, v90
	v_rcp_f32_e32 v103, v103
	v_max_f32_e32 v90, 1.0, v90
	v_mul_f32_e32 v99, 0x437f0000, v99
	v_rndne_f32_e32 v90, v90
	v_max_f32_e32 v99, 1.0, v99
	v_cvt_pk_u8_f32 v90, v90, 0, 0
	v_mul_f32_e32 v91, 0x437f0000, v91
	v_rndne_f32_e32 v99, v99
	v_max_f32_e32 v91, 1.0, v91
	v_cvt_pk_u8_f32 v90, v99, 1, v90
	v_mul_f32_e32 v99, 0xbfb8aa3b, v96
	v_mul_f32_e32 v103, 0x437f0000, v103
	v_rndne_f32_e32 v91, v91
	v_exp_f32_e32 v99, v99
	v_max_f32_e32 v103, 1.0, v103
	v_cvt_pk_u8_f32 v91, v91, 0, 0
	v_rndne_f32_e32 v103, v103
	v_cvt_pk_u8_f32 v91, v103, 1, v91
	v_mul_f32_e32 v103, 0xbfb8aa3b, v92
	v_exp_f32_e32 v103, v103
	v_add_f32_e32 v99, 1.0, v99
	v_rcp_f32_e32 v99, v99
	v_mul_f32_e32 v104, 0xbfb8aa3b, v97
	v_add_f32_e32 v103, 1.0, v103
	v_rcp_f32_e32 v103, v103
	v_exp_f32_e32 v104, v104
	v_mul_f32_e32 v99, 0x437f0000, v99
	v_max_f32_e32 v99, 1.0, v99
	v_rndne_f32_e32 v99, v99
	v_cvt_pk_u8_f32 v90, v99, 2, v90
	v_mul_f32_e32 v99, 0x437f0000, v103
	v_add_f32_e32 v103, 1.0, v104
	v_mul_f32_e32 v104, 0xbfb8aa3b, v93
	v_rcp_f32_e32 v103, v103
	v_exp_f32_e32 v104, v104
	v_max_f32_e32 v99, 1.0, v99
	v_rndne_f32_e32 v99, v99
	v_cvt_pk_u8_f32 v91, v99, 2, v91
	v_mul_f32_e32 v99, 0x437f0000, v103
	v_add_f32_e32 v103, 1.0, v104
	v_rcp_f32_e32 v103, v103
	v_max_f32_e32 v99, 1.0, v99
	v_rndne_f32_e32 v99, v99
	v_cvt_pk_u8_f32 v90, v99, 3, v90
	v_mul_f32_e32 v99, 0x437f0000, v103
	v_max_f32_e32 v99, 1.0, v99
	v_mov_b64_e32 v[104:105], s[30:31]
	v_rndne_f32_e32 v99, v99
	v_mad_i64_i32 v[104:105], s[0:1], v102, s55, v[104:105]
	v_cvt_pk_u8_f32 v91, v99, 3, v91
	v_lshl_add_u64 v[104:105], v[104:105], 0, v[140:141]
	s_mov_b64 s[0:1], 0
	v_mov_b32_e32 v246, v90
	v_mov_b32_e32 v247, v91

.LBB0_721:
	v_mov_b32_e32 v99, v98
	v_mov_b32_e32 v92, v98
	v_mov_b32_e32 v93, v98
	v_pk_mul_f32 v[88:89], v[88:89], v[92:93]
	v_pk_mul_f32 v[86:87], v[86:87], v[98:99]
	v_pk_mul_f32 v[84:85], v[84:85], v[92:93]
	v_pk_mul_f32 v[82:83], v[82:83], v[98:99]
	s_and_b64 vcc, exec, s[42:43]
	s_mov_b64 s[0:1], -1
	s_cbranch_vccnz .LBB0_723
	v_mul_f32_e32 v92, 0xbfb8aa3b, v86
	v_exp_f32_e32 v92, v92
	v_mul_f32_e32 v94, 0xbfb8aa3b, v87
	v_exp_f32_e32 v94, v94
	v_mul_f32_e32 v93, 0xbfb8aa3b, v82
	v_exp_f32_e32 v93, v93
	v_mul_f32_e32 v95, 0xbfb8aa3b, v83
	v_add_f32_e32 v92, 1.0, v92
	v_exp_f32_e32 v95, v95
	v_rcp_f32_e32 v92, v92
	v_add_f32_e32 v94, 1.0, v94
	v_rcp_f32_e32 v94, v94
	v_add_f32_e32 v93, 1.0, v93
	v_rcp_f32_e32 v93, v93
	v_add_f32_e32 v95, 1.0, v95
	v_mul_f32_e32 v92, 0x437f0000, v92
	v_rcp_f32_e32 v95, v95
	v_max_f32_e32 v92, 1.0, v92
	v_mul_f32_e32 v94, 0x437f0000, v94
	v_rndne_f32_e32 v92, v92
	v_max_f32_e32 v94, 1.0, v94
	v_cvt_pk_u8_f32 v92, v92, 0, 0
	v_mul_f32_e32 v93, 0x437f0000, v93
	v_rndne_f32_e32 v94, v94
	v_max_f32_e32 v93, 1.0, v93
	v_cvt_pk_u8_f32 v92, v94, 1, v92
	v_mul_f32_e32 v94, 0xbfb8aa3b, v88
	v_mul_f32_e32 v95, 0x437f0000, v95
	v_rndne_f32_e32 v93, v93
	v_exp_f32_e32 v94, v94
	v_max_f32_e32 v95, 1.0, v95
	v_cvt_pk_u8_f32 v93, v93, 0, 0
	v_rndne_f32_e32 v95, v95
	v_cvt_pk_u8_f32 v93, v95, 1, v93
	v_mul_f32_e32 v95, 0xbfb8aa3b, v84
	v_exp_f32_e32 v95, v95
	v_add_f32_e32 v94, 1.0, v94
	v_rcp_f32_e32 v94, v94
	v_mul_f32_e32 v96, 0xbfb8aa3b, v89
	v_add_f32_e32 v95, 1.0, v95
	v_rcp_f32_e32 v95, v95
	v_exp_f32_e32 v96, v96
	v_mul_f32_e32 v94, 0x437f0000, v94
	v_max_f32_e32 v94, 1.0, v94
	v_rndne_f32_e32 v94, v94
	v_cvt_pk_u8_f32 v92, v94, 2, v92
	v_mul_f32_e32 v94, 0x437f0000, v95
	v_add_f32_e32 v95, 1.0, v96
	v_mul_f32_e32 v96, 0xbfb8aa3b, v85
	v_rcp_f32_e32 v95, v95
	v_exp_f32_e32 v96, v96
	v_max_f32_e32 v94, 1.0, v94
	v_rndne_f32_e32 v94, v94
	v_cvt_pk_u8_f32 v93, v94, 2, v93
	v_mul_f32_e32 v94, 0x437f0000, v95
	v_add_f32_e32 v95, 1.0, v96
	v_rcp_f32_e32 v95, v95
	v_max_f32_e32 v94, 1.0, v94
	v_rndne_f32_e32 v94, v94
	v_cvt_pk_u8_f32 v92, v94, 3, v92
	v_mul_f32_e32 v94, 0x437f0000, v95
	v_max_f32_e32 v94, 1.0, v94
	v_rndne_f32_e32 v94, v94
	v_cvt_pk_u8_f32 v93, v94, 3, v93
	v_mov_b64_e32 v[94:95], s[30:31]
	v_mad_i64_i32 v[94:95], s[0:1], v102, s55, v[94:95]
	v_lshl_add_u64 v[94:95], v[94:95], 0, v[140:141]
	s_mov_b64 s[0:1], 0
	v_mov_b32_e32 v244, v92
	v_mov_b32_e32 v245, v93
	v_mov_b32_e32 v250, v176
	v_mov_b32_e32 v251, 0
	v_lshl_add_u64 v[94:95], v[94:95], 0, v[250:251]
	global_store_dwordx4 v[94:95], v[244:247], off

.LBB0_725:
	v_ffbh_u32_e32 v82, v153
	v_min_u32_e32 v84, 32, v82
	v_lshlrev_b64 v[82:83], v84, v[152:153]
	v_min_u32_e32 v82, 1, v82
	v_or_b32_e32 v82, v83, v82
	v_cvt_f32_u32_e32 v82, v82
	v_sub_u32_e32 v83, 32, v84
	v_or_b32_e32 v86, 48, v142
	s_mov_b64 s[0:1], -1
	v_ldexp_f32 v82, v82, v83
	v_mul_f32_e32 v82, 0x33800000, v82
	v_fmamk_f32 v82, v82, 0x3a800000, v210
	v_mul_f32_e32 v83, 0x4b800000, v82
	v_cmp_gt_f32_e32 vcc, s34, v82
	s_nop 1
	v_cndmask_b32_e32 v82, v82, v83, vcc
	v_rsq_f32_e32 v82, v82
	s_nop 0
	v_mul_f32_e32 v83, 0x45800000, v82
	v_cndmask_b32_e32 v82, v82, v83, vcc
	v_pk_mul_f32 v[80:81], v[80:81], v[82:83] op_sel_hi:[1,0]
	v_pk_mul_f32 v[84:85], v[78:79], v[82:83] op_sel_hi:[1,0]
	v_pk_mul_f32 v[76:77], v[76:77], v[82:83] op_sel_hi:[1,0]
	v_pk_mul_f32 v[78:79], v[74:75], v[82:83] op_sel_hi:[1,0]
	s_and_b64 vcc, exec, s[42:43]
	s_cbranch_vccnz .LBB0_727
	v_mul_f32_e32 v74, 0xbfb8aa3b, v84
	v_exp_f32_e32 v74, v74
	v_mul_f32_e32 v83, 0xbfb8aa3b, v85
	v_exp_f32_e32 v83, v83
	v_mul_f32_e32 v75, 0xbfb8aa3b, v78
	v_exp_f32_e32 v75, v75
	v_mul_f32_e32 v87, 0xbfb8aa3b, v79
	v_add_f32_e32 v74, 1.0, v74
	v_exp_f32_e32 v87, v87
	v_rcp_f32_e32 v74, v74
	v_add_f32_e32 v83, 1.0, v83
	v_rcp_f32_e32 v83, v83
	v_add_f32_e32 v75, 1.0, v75
	v_rcp_f32_e32 v75, v75
	v_add_f32_e32 v87, 1.0, v87
	v_mul_f32_e32 v74, 0x437f0000, v74
	v_rcp_f32_e32 v87, v87
	v_max_f32_e32 v74, 1.0, v74
	v_mul_f32_e32 v83, 0x437f0000, v83
	v_rndne_f32_e32 v74, v74
	v_max_f32_e32 v83, 1.0, v83
	v_cvt_pk_u8_f32 v74, v74, 0, 0
	v_mul_f32_e32 v75, 0x437f0000, v75
	v_rndne_f32_e32 v83, v83
	v_max_f32_e32 v75, 1.0, v75
	v_cvt_pk_u8_f32 v74, v83, 1, v74
	v_mul_f32_e32 v83, 0xbfb8aa3b, v80
	v_mul_f32_e32 v87, 0x437f0000, v87
	v_rndne_f32_e32 v75, v75
	v_exp_f32_e32 v83, v83
	v_max_f32_e32 v87, 1.0, v87
	v_cvt_pk_u8_f32 v75, v75, 0, 0
	v_rndne_f32_e32 v87, v87
	v_cvt_pk_u8_f32 v75, v87, 1, v75
	v_mul_f32_e32 v87, 0xbfb8aa3b, v76
	v_exp_f32_e32 v87, v87
	v_add_f32_e32 v83, 1.0, v83
	v_rcp_f32_e32 v83, v83
	v_mul_f32_e32 v88, 0xbfb8aa3b, v81
	v_add_f32_e32 v87, 1.0, v87
	v_rcp_f32_e32 v87, v87
	v_exp_f32_e32 v88, v88
	v_mul_f32_e32 v83, 0x437f0000, v83
	v_max_f32_e32 v83, 1.0, v83
	v_rndne_f32_e32 v83, v83
	v_cvt_pk_u8_f32 v74, v83, 2, v74
	v_mul_f32_e32 v83, 0x437f0000, v87
	v_add_f32_e32 v87, 1.0, v88
	v_mul_f32_e32 v88, 0xbfb8aa3b, v77
	v_rcp_f32_e32 v87, v87
	v_exp_f32_e32 v88, v88
	v_max_f32_e32 v83, 1.0, v83
	v_rndne_f32_e32 v83, v83
	v_cvt_pk_u8_f32 v75, v83, 2, v75
	v_mul_f32_e32 v83, 0x437f0000, v87
	v_add_f32_e32 v87, 1.0, v88
	v_rcp_f32_e32 v87, v87
	v_max_f32_e32 v83, 1.0, v83
	v_rndne_f32_e32 v83, v83
	v_cvt_pk_u8_f32 v74, v83, 3, v74
	v_mul_f32_e32 v83, 0x437f0000, v87
	v_max_f32_e32 v83, 1.0, v83
	v_mov_b64_e32 v[88:89], s[30:31]
	v_rndne_f32_e32 v83, v83
	v_mad_i64_i32 v[88:89], s[0:1], v86, s55, v[88:89]
	v_cvt_pk_u8_f32 v75, v83, 3, v75
	v_lshl_add_u64 v[88:89], v[88:89], 0, v[140:141]
	s_mov_b64 s[0:1], 0
	v_mov_b32_e32 v246, v74
	v_mov_b32_e32 v247, v75

.LBB0_729:
	v_mov_b32_e32 v83, v82
	v_mov_b32_e32 v76, v82
	v_mov_b32_e32 v77, v82
	v_pk_mul_f32 v[72:73], v[72:73], v[76:77]
	v_pk_mul_f32 v[70:71], v[70:71], v[82:83]
	v_pk_mul_f32 v[68:69], v[68:69], v[76:77]
	v_pk_mul_f32 v[66:67], v[66:67], v[82:83]
	s_and_b64 vcc, exec, s[42:43]
	s_mov_b64 s[0:1], -1
	s_cbranch_vccnz .LBB0_731
	v_mul_f32_e32 v76, 0xbfb8aa3b, v70
	v_exp_f32_e32 v76, v76
	v_mul_f32_e32 v78, 0xbfb8aa3b, v71
	v_exp_f32_e32 v78, v78
	v_mul_f32_e32 v77, 0xbfb8aa3b, v66
	v_exp_f32_e32 v77, v77
	v_mul_f32_e32 v79, 0xbfb8aa3b, v67
	v_add_f32_e32 v76, 1.0, v76
	v_exp_f32_e32 v79, v79
	v_rcp_f32_e32 v76, v76
	v_add_f32_e32 v78, 1.0, v78
	v_rcp_f32_e32 v78, v78
	v_add_f32_e32 v77, 1.0, v77
	v_rcp_f32_e32 v77, v77
	v_add_f32_e32 v79, 1.0, v79
	v_mul_f32_e32 v76, 0x437f0000, v76
	v_rcp_f32_e32 v79, v79
	v_max_f32_e32 v76, 1.0, v76
	v_mul_f32_e32 v78, 0x437f0000, v78
	v_rndne_f32_e32 v76, v76
	v_max_f32_e32 v78, 1.0, v78
	v_cvt_pk_u8_f32 v76, v76, 0, 0
	v_mul_f32_e32 v77, 0x437f0000, v77
	v_rndne_f32_e32 v78, v78
	v_max_f32_e32 v77, 1.0, v77
	v_cvt_pk_u8_f32 v76, v78, 1, v76
	v_mul_f32_e32 v78, 0xbfb8aa3b, v72
	v_mul_f32_e32 v79, 0x437f0000, v79
	v_rndne_f32_e32 v77, v77
	v_exp_f32_e32 v78, v78
	v_max_f32_e32 v79, 1.0, v79
	v_cvt_pk_u8_f32 v77, v77, 0, 0
	v_rndne_f32_e32 v79, v79
	v_cvt_pk_u8_f32 v77, v79, 1, v77
	v_mul_f32_e32 v79, 0xbfb8aa3b, v68
	v_exp_f32_e32 v79, v79
	v_add_f32_e32 v78, 1.0, v78
	v_rcp_f32_e32 v78, v78
	v_mul_f32_e32 v80, 0xbfb8aa3b, v73
	v_add_f32_e32 v79, 1.0, v79
	v_rcp_f32_e32 v79, v79
	v_exp_f32_e32 v80, v80
	v_mul_f32_e32 v78, 0x437f0000, v78
	v_max_f32_e32 v78, 1.0, v78
	v_rndne_f32_e32 v78, v78
	v_cvt_pk_u8_f32 v76, v78, 2, v76
	v_mul_f32_e32 v78, 0x437f0000, v79
	v_add_f32_e32 v79, 1.0, v80
	v_mul_f32_e32 v80, 0xbfb8aa3b, v69
	v_rcp_f32_e32 v79, v79
	v_exp_f32_e32 v80, v80
	v_max_f32_e32 v78, 1.0, v78
	v_rndne_f32_e32 v78, v78
	v_cvt_pk_u8_f32 v77, v78, 2, v77
	v_mul_f32_e32 v78, 0x437f0000, v79
	v_add_f32_e32 v79, 1.0, v80
	v_rcp_f32_e32 v79, v79
	v_max_f32_e32 v78, 1.0, v78
	v_rndne_f32_e32 v78, v78
	v_cvt_pk_u8_f32 v76, v78, 3, v76
	v_mul_f32_e32 v78, 0x437f0000, v79
	v_max_f32_e32 v78, 1.0, v78
	v_rndne_f32_e32 v78, v78
	v_cvt_pk_u8_f32 v77, v78, 3, v77
	v_mov_b64_e32 v[78:79], s[30:31]
	v_mad_i64_i32 v[78:79], s[0:1], v86, s55, v[78:79]
	v_lshl_add_u64 v[78:79], v[78:79], 0, v[140:141]
	s_mov_b64 s[0:1], 0
	v_mov_b32_e32 v244, v76
	v_mov_b32_e32 v245, v77
	v_mov_b32_e32 v250, v176
	v_mov_b32_e32 v251, 0
	v_lshl_add_u64 v[78:79], v[78:79], 0, v[250:251]
	global_store_dwordx4 v[78:79], v[244:247], off

.LBB0_733:
	v_ffbh_u32_e32 v66, v151
	v_min_u32_e32 v68, 32, v66
	v_lshlrev_b64 v[66:67], v68, v[150:151]
	v_min_u32_e32 v66, 1, v66
	v_or_b32_e32 v66, v67, v66
	v_cvt_f32_u32_e32 v66, v66
	v_sub_u32_e32 v67, 32, v68
	v_add_u32_e32 v70, 0x80, v142
	s_mov_b64 s[0:1], -1
	v_ldexp_f32 v66, v66, v67
	v_mul_f32_e32 v66, 0x33800000, v66
	v_fmamk_f32 v66, v66, 0x3a800000, v210
	v_mul_f32_e32 v67, 0x4b800000, v66
	v_cmp_gt_f32_e32 vcc, s34, v66
	s_nop 1
	v_cndmask_b32_e32 v66, v66, v67, vcc
	v_rsq_f32_e32 v66, v66
	s_nop 0
	v_mul_f32_e32 v67, 0x45800000, v66
	v_cndmask_b32_e32 v66, v66, v67, vcc
	v_pk_mul_f32 v[64:65], v[64:65], v[66:67] op_sel_hi:[1,0]
	v_pk_mul_f32 v[68:69], v[62:63], v[66:67] op_sel_hi:[1,0]
	v_pk_mul_f32 v[60:61], v[60:61], v[66:67] op_sel_hi:[1,0]
	v_pk_mul_f32 v[62:63], v[58:59], v[66:67] op_sel_hi:[1,0]
	s_and_b64 vcc, exec, s[42:43]
	s_cbranch_vccnz .LBB0_735
	v_mul_f32_e32 v58, 0xbfb8aa3b, v68
	v_exp_f32_e32 v58, v58
	v_mul_f32_e32 v67, 0xbfb8aa3b, v69
	v_exp_f32_e32 v67, v67
	v_mul_f32_e32 v59, 0xbfb8aa3b, v62
	v_exp_f32_e32 v59, v59
	v_mul_f32_e32 v71, 0xbfb8aa3b, v63
	v_add_f32_e32 v58, 1.0, v58
	v_exp_f32_e32 v71, v71
	v_rcp_f32_e32 v58, v58
	v_add_f32_e32 v67, 1.0, v67
	v_rcp_f32_e32 v67, v67
	v_add_f32_e32 v59, 1.0, v59
	v_rcp_f32_e32 v59, v59
	v_add_f32_e32 v71, 1.0, v71
	v_mul_f32_e32 v58, 0x437f0000, v58
	v_rcp_f32_e32 v71, v71
	v_max_f32_e32 v58, 1.0, v58
	v_mul_f32_e32 v67, 0x437f0000, v67
	v_rndne_f32_e32 v58, v58
	v_max_f32_e32 v67, 1.0, v67
	v_cvt_pk_u8_f32 v58, v58, 0, 0
	v_mul_f32_e32 v59, 0x437f0000, v59
	v_rndne_f32_e32 v67, v67
	v_max_f32_e32 v59, 1.0, v59
	v_cvt_pk_u8_f32 v58, v67, 1, v58
	v_mul_f32_e32 v67, 0xbfb8aa3b, v64
	v_mul_f32_e32 v71, 0x437f0000, v71
	v_rndne_f32_e32 v59, v59
	v_exp_f32_e32 v67, v67
	v_max_f32_e32 v71, 1.0, v71
	v_cvt_pk_u8_f32 v59, v59, 0, 0
	v_rndne_f32_e32 v71, v71
	v_cvt_pk_u8_f32 v59, v71, 1, v59
	v_mul_f32_e32 v71, 0xbfb8aa3b, v60
	v_exp_f32_e32 v71, v71
	v_add_f32_e32 v67, 1.0, v67
	v_rcp_f32_e32 v67, v67
	v_mul_f32_e32 v72, 0xbfb8aa3b, v65
	v_add_f32_e32 v71, 1.0, v71
	v_rcp_f32_e32 v71, v71
	v_exp_f32_e32 v72, v72
	v_mul_f32_e32 v67, 0x437f0000, v67
	v_max_f32_e32 v67, 1.0, v67
	v_rndne_f32_e32 v67, v67
	v_cvt_pk_u8_f32 v58, v67, 2, v58
	v_mul_f32_e32 v67, 0x437f0000, v71
	v_add_f32_e32 v71, 1.0, v72
	v_mul_f32_e32 v72, 0xbfb8aa3b, v61
	v_rcp_f32_e32 v71, v71
	v_exp_f32_e32 v72, v72
	v_max_f32_e32 v67, 1.0, v67
	v_rndne_f32_e32 v67, v67
	v_cvt_pk_u8_f32 v59, v67, 2, v59
	v_mul_f32_e32 v67, 0x437f0000, v71
	v_add_f32_e32 v71, 1.0, v72
	v_rcp_f32_e32 v71, v71
	v_max_f32_e32 v67, 1.0, v67
	v_rndne_f32_e32 v67, v67
	v_cvt_pk_u8_f32 v58, v67, 3, v58
	v_mul_f32_e32 v67, 0x437f0000, v71
	v_max_f32_e32 v67, 1.0, v67
	v_mov_b64_e32 v[72:73], s[30:31]
	v_rndne_f32_e32 v67, v67
	v_mad_i64_i32 v[72:73], s[0:1], v70, s55, v[72:73]
	v_cvt_pk_u8_f32 v59, v67, 3, v59
	v_lshl_add_u64 v[72:73], v[72:73], 0, v[140:141]
	s_mov_b64 s[0:1], 0
	v_mov_b32_e32 v246, v58
	v_mov_b32_e32 v247, v59

.LBB0_737:
	v_mov_b32_e32 v67, v66
	v_mov_b32_e32 v60, v66
	v_mov_b32_e32 v61, v66
	v_pk_mul_f32 v[56:57], v[56:57], v[60:61]
	v_pk_mul_f32 v[54:55], v[54:55], v[66:67]
	v_pk_mul_f32 v[52:53], v[52:53], v[60:61]
	v_pk_mul_f32 v[50:51], v[50:51], v[66:67]
	s_and_b64 vcc, exec, s[42:43]
	s_mov_b64 s[0:1], -1
	s_cbranch_vccnz .LBB0_739
	v_mul_f32_e32 v60, 0xbfb8aa3b, v54
	v_exp_f32_e32 v60, v60
	v_mul_f32_e32 v62, 0xbfb8aa3b, v55
	v_exp_f32_e32 v62, v62
	v_mul_f32_e32 v61, 0xbfb8aa3b, v50
	v_exp_f32_e32 v61, v61
	v_mul_f32_e32 v63, 0xbfb8aa3b, v51
	v_add_f32_e32 v60, 1.0, v60
	v_exp_f32_e32 v63, v63
	v_rcp_f32_e32 v60, v60
	v_add_f32_e32 v62, 1.0, v62
	v_rcp_f32_e32 v62, v62
	v_add_f32_e32 v61, 1.0, v61
	v_rcp_f32_e32 v61, v61
	v_add_f32_e32 v63, 1.0, v63
	v_mul_f32_e32 v60, 0x437f0000, v60
	v_rcp_f32_e32 v63, v63
	v_max_f32_e32 v60, 1.0, v60
	v_mul_f32_e32 v62, 0x437f0000, v62
	v_rndne_f32_e32 v60, v60
	v_max_f32_e32 v62, 1.0, v62
	v_cvt_pk_u8_f32 v60, v60, 0, 0
	v_mul_f32_e32 v61, 0x437f0000, v61
	v_rndne_f32_e32 v62, v62
	v_max_f32_e32 v61, 1.0, v61
	v_cvt_pk_u8_f32 v60, v62, 1, v60
	v_mul_f32_e32 v62, 0xbfb8aa3b, v56
	v_mul_f32_e32 v63, 0x437f0000, v63
	v_rndne_f32_e32 v61, v61
	v_exp_f32_e32 v62, v62
	v_max_f32_e32 v63, 1.0, v63
	v_cvt_pk_u8_f32 v61, v61, 0, 0
	v_rndne_f32_e32 v63, v63
	v_cvt_pk_u8_f32 v61, v63, 1, v61
	v_mul_f32_e32 v63, 0xbfb8aa3b, v52
	v_exp_f32_e32 v63, v63
	v_add_f32_e32 v62, 1.0, v62
	v_rcp_f32_e32 v62, v62
	v_mul_f32_e32 v64, 0xbfb8aa3b, v57
	v_add_f32_e32 v63, 1.0, v63
	v_rcp_f32_e32 v63, v63
	v_exp_f32_e32 v64, v64
	v_mul_f32_e32 v62, 0x437f0000, v62
	v_max_f32_e32 v62, 1.0, v62
	v_rndne_f32_e32 v62, v62
	v_cvt_pk_u8_f32 v60, v62, 2, v60
	v_mul_f32_e32 v62, 0x437f0000, v63
	v_add_f32_e32 v63, 1.0, v64
	v_mul_f32_e32 v64, 0xbfb8aa3b, v53
	v_rcp_f32_e32 v63, v63
	v_exp_f32_e32 v64, v64
	v_max_f32_e32 v62, 1.0, v62
	v_rndne_f32_e32 v62, v62
	v_cvt_pk_u8_f32 v61, v62, 2, v61
	v_mul_f32_e32 v62, 0x437f0000, v63
	v_add_f32_e32 v63, 1.0, v64
	v_rcp_f32_e32 v63, v63
	v_max_f32_e32 v62, 1.0, v62
	v_rndne_f32_e32 v62, v62
	v_cvt_pk_u8_f32 v60, v62, 3, v60
	v_mul_f32_e32 v62, 0x437f0000, v63
	v_max_f32_e32 v62, 1.0, v62
	v_rndne_f32_e32 v62, v62
	v_cvt_pk_u8_f32 v61, v62, 3, v61
	v_mov_b64_e32 v[62:63], s[30:31]
	v_mad_i64_i32 v[62:63], s[0:1], v70, s55, v[62:63]
	v_lshl_add_u64 v[62:63], v[62:63], 0, v[140:141]
	s_mov_b64 s[0:1], 0
	v_mov_b32_e32 v244, v60
	v_mov_b32_e32 v245, v61
	v_mov_b32_e32 v250, v176
	v_mov_b32_e32 v251, 0
	v_lshl_add_u64 v[62:63], v[62:63], 0, v[250:251]
	global_store_dwordx4 v[62:63], v[244:247], off

.LBB0_741:
	v_ffbh_u32_e32 v50, v149
	v_min_u32_e32 v52, 32, v50
	v_lshlrev_b64 v[50:51], v52, v[148:149]
	v_min_u32_e32 v50, 1, v50
	v_or_b32_e32 v50, v51, v50
	v_cvt_f32_u32_e32 v50, v50
	v_sub_u32_e32 v51, 32, v52
	v_add_u32_e32 v54, 0x90, v142
	s_mov_b64 s[0:1], -1
	v_ldexp_f32 v50, v50, v51
	v_mul_f32_e32 v50, 0x33800000, v50
	v_fmamk_f32 v50, v50, 0x3a800000, v210
	v_mul_f32_e32 v51, 0x4b800000, v50
	v_cmp_gt_f32_e32 vcc, s34, v50
	s_nop 1
	v_cndmask_b32_e32 v50, v50, v51, vcc
	v_rsq_f32_e32 v50, v50
	s_nop 0
	v_mul_f32_e32 v51, 0x45800000, v50
	v_cndmask_b32_e32 v50, v50, v51, vcc
	v_pk_mul_f32 v[48:49], v[48:49], v[50:51] op_sel_hi:[1,0]
	v_pk_mul_f32 v[52:53], v[46:47], v[50:51] op_sel_hi:[1,0]
	v_pk_mul_f32 v[44:45], v[44:45], v[50:51] op_sel_hi:[1,0]
	v_pk_mul_f32 v[46:47], v[42:43], v[50:51] op_sel_hi:[1,0]
	s_and_b64 vcc, exec, s[42:43]
	s_cbranch_vccnz .LBB0_743
	v_mul_f32_e32 v42, 0xbfb8aa3b, v52
	v_exp_f32_e32 v42, v42
	v_mul_f32_e32 v51, 0xbfb8aa3b, v53
	v_exp_f32_e32 v51, v51
	v_mul_f32_e32 v43, 0xbfb8aa3b, v46
	v_exp_f32_e32 v43, v43
	v_mul_f32_e32 v55, 0xbfb8aa3b, v47
	v_add_f32_e32 v42, 1.0, v42
	v_exp_f32_e32 v55, v55
	v_rcp_f32_e32 v42, v42
	v_add_f32_e32 v51, 1.0, v51
	v_rcp_f32_e32 v51, v51
	v_add_f32_e32 v43, 1.0, v43
	v_rcp_f32_e32 v43, v43
	v_add_f32_e32 v55, 1.0, v55
	v_mul_f32_e32 v42, 0x437f0000, v42
	v_rcp_f32_e32 v55, v55
	v_max_f32_e32 v42, 1.0, v42
	v_mul_f32_e32 v51, 0x437f0000, v51
	v_rndne_f32_e32 v42, v42
	v_max_f32_e32 v51, 1.0, v51
	v_cvt_pk_u8_f32 v42, v42, 0, 0
	v_mul_f32_e32 v43, 0x437f0000, v43
	v_rndne_f32_e32 v51, v51
	v_max_f32_e32 v43, 1.0, v43
	v_cvt_pk_u8_f32 v42, v51, 1, v42
	v_mul_f32_e32 v51, 0xbfb8aa3b, v48
	v_mul_f32_e32 v55, 0x437f0000, v55
	v_rndne_f32_e32 v43, v43
	v_exp_f32_e32 v51, v51
	v_max_f32_e32 v55, 1.0, v55
	v_cvt_pk_u8_f32 v43, v43, 0, 0
	v_rndne_f32_e32 v55, v55
	v_cvt_pk_u8_f32 v43, v55, 1, v43
	v_mul_f32_e32 v55, 0xbfb8aa3b, v44
	v_exp_f32_e32 v55, v55
	v_add_f32_e32 v51, 1.0, v51
	v_rcp_f32_e32 v51, v51
	v_mul_f32_e32 v56, 0xbfb8aa3b, v49
	v_add_f32_e32 v55, 1.0, v55
	v_rcp_f32_e32 v55, v55
	v_exp_f32_e32 v56, v56
	v_mul_f32_e32 v51, 0x437f0000, v51
	v_max_f32_e32 v51, 1.0, v51
	v_rndne_f32_e32 v51, v51
	v_cvt_pk_u8_f32 v42, v51, 2, v42
	v_mul_f32_e32 v51, 0x437f0000, v55
	v_add_f32_e32 v55, 1.0, v56
	v_mul_f32_e32 v56, 0xbfb8aa3b, v45
	v_rcp_f32_e32 v55, v55
	v_exp_f32_e32 v56, v56
	v_max_f32_e32 v51, 1.0, v51
	v_rndne_f32_e32 v51, v51
	v_cvt_pk_u8_f32 v43, v51, 2, v43
	v_mul_f32_e32 v51, 0x437f0000, v55
	v_add_f32_e32 v55, 1.0, v56
	v_rcp_f32_e32 v55, v55
	v_max_f32_e32 v51, 1.0, v51
	v_rndne_f32_e32 v51, v51
	v_cvt_pk_u8_f32 v42, v51, 3, v42
	v_mul_f32_e32 v51, 0x437f0000, v55
	v_max_f32_e32 v51, 1.0, v51
	v_mov_b64_e32 v[56:57], s[30:31]
	v_rndne_f32_e32 v51, v51
	v_mad_i64_i32 v[56:57], s[0:1], v54, s55, v[56:57]
	v_cvt_pk_u8_f32 v43, v51, 3, v43
	v_lshl_add_u64 v[56:57], v[56:57], 0, v[140:141]
	s_mov_b64 s[0:1], 0
	v_mov_b32_e32 v246, v42
	v_mov_b32_e32 v247, v43

.LBB0_745:
	v_mov_b32_e32 v51, v50
	v_mov_b32_e32 v44, v50
	v_mov_b32_e32 v45, v50
	v_pk_mul_f32 v[40:41], v[40:41], v[44:45]
	v_pk_mul_f32 v[38:39], v[38:39], v[50:51]
	v_pk_mul_f32 v[36:37], v[36:37], v[44:45]
	v_pk_mul_f32 v[34:35], v[34:35], v[50:51]
	s_and_b64 vcc, exec, s[42:43]
	s_mov_b64 s[0:1], -1
	s_cbranch_vccnz .LBB0_747
	v_mul_f32_e32 v44, 0xbfb8aa3b, v38
	v_exp_f32_e32 v44, v44
	v_mul_f32_e32 v46, 0xbfb8aa3b, v39
	v_exp_f32_e32 v46, v46
	v_mul_f32_e32 v45, 0xbfb8aa3b, v34
	v_exp_f32_e32 v45, v45
	v_mul_f32_e32 v47, 0xbfb8aa3b, v35
	v_add_f32_e32 v44, 1.0, v44
	v_exp_f32_e32 v47, v47
	v_rcp_f32_e32 v44, v44
	v_add_f32_e32 v46, 1.0, v46
	v_rcp_f32_e32 v46, v46
	v_add_f32_e32 v45, 1.0, v45
	v_rcp_f32_e32 v45, v45
	v_add_f32_e32 v47, 1.0, v47
	v_mul_f32_e32 v44, 0x437f0000, v44
	v_rcp_f32_e32 v47, v47
	v_max_f32_e32 v44, 1.0, v44
	v_mul_f32_e32 v46, 0x437f0000, v46
	v_rndne_f32_e32 v44, v44
	v_max_f32_e32 v46, 1.0, v46
	v_cvt_pk_u8_f32 v44, v44, 0, 0
	v_mul_f32_e32 v45, 0x437f0000, v45
	v_rndne_f32_e32 v46, v46
	v_max_f32_e32 v45, 1.0, v45
	v_cvt_pk_u8_f32 v44, v46, 1, v44
	v_mul_f32_e32 v46, 0xbfb8aa3b, v40
	v_mul_f32_e32 v47, 0x437f0000, v47
	v_rndne_f32_e32 v45, v45
	v_exp_f32_e32 v46, v46
	v_max_f32_e32 v47, 1.0, v47
	v_cvt_pk_u8_f32 v45, v45, 0, 0
	v_rndne_f32_e32 v47, v47
	v_cvt_pk_u8_f32 v45, v47, 1, v45
	v_mul_f32_e32 v47, 0xbfb8aa3b, v36
	v_exp_f32_e32 v47, v47
	v_add_f32_e32 v46, 1.0, v46
	v_rcp_f32_e32 v46, v46
	v_mul_f32_e32 v48, 0xbfb8aa3b, v41
	v_add_f32_e32 v47, 1.0, v47
	v_rcp_f32_e32 v47, v47
	v_exp_f32_e32 v48, v48
	v_mul_f32_e32 v46, 0x437f0000, v46
	v_max_f32_e32 v46, 1.0, v46
	v_rndne_f32_e32 v46, v46
	v_cvt_pk_u8_f32 v44, v46, 2, v44
	v_mul_f32_e32 v46, 0x437f0000, v47
	v_add_f32_e32 v47, 1.0, v48
	v_mul_f32_e32 v48, 0xbfb8aa3b, v37
	v_rcp_f32_e32 v47, v47
	v_exp_f32_e32 v48, v48
	v_max_f32_e32 v46, 1.0, v46
	v_rndne_f32_e32 v46, v46
	v_cvt_pk_u8_f32 v45, v46, 2, v45
	v_mul_f32_e32 v46, 0x437f0000, v47
	v_add_f32_e32 v47, 1.0, v48
	v_rcp_f32_e32 v47, v47
	v_max_f32_e32 v46, 1.0, v46
	v_rndne_f32_e32 v46, v46
	v_cvt_pk_u8_f32 v44, v46, 3, v44
	v_mul_f32_e32 v46, 0x437f0000, v47
	v_max_f32_e32 v46, 1.0, v46
	v_rndne_f32_e32 v46, v46
	v_cvt_pk_u8_f32 v45, v46, 3, v45
	v_mov_b64_e32 v[46:47], s[30:31]
	v_mad_i64_i32 v[46:47], s[0:1], v54, s55, v[46:47]
	v_lshl_add_u64 v[46:47], v[46:47], 0, v[140:141]
	s_mov_b64 s[0:1], 0
	v_mov_b32_e32 v244, v44
	v_mov_b32_e32 v245, v45
	v_mov_b32_e32 v250, v176
	v_mov_b32_e32 v251, 0
	v_lshl_add_u64 v[46:47], v[46:47], 0, v[250:251]
	global_store_dwordx4 v[46:47], v[244:247], off

.LBB0_749:
	v_ffbh_u32_e32 v34, v147
	v_min_u32_e32 v36, 32, v34
	v_lshlrev_b64 v[34:35], v36, v[146:147]
	v_min_u32_e32 v34, 1, v34
	v_or_b32_e32 v34, v35, v34
	v_cvt_f32_u32_e32 v34, v34
	v_sub_u32_e32 v35, 32, v36
	v_add_u32_e32 v38, 0xa0, v142
	s_mov_b64 s[0:1], -1
	v_ldexp_f32 v34, v34, v35
	v_mul_f32_e32 v34, 0x33800000, v34
	v_fmamk_f32 v34, v34, 0x3a800000, v210
	v_mul_f32_e32 v35, 0x4b800000, v34
	v_cmp_gt_f32_e32 vcc, s34, v34
	s_nop 1
	v_cndmask_b32_e32 v34, v34, v35, vcc
	v_rsq_f32_e32 v34, v34
	s_nop 0
	v_mul_f32_e32 v35, 0x45800000, v34
	v_cndmask_b32_e32 v34, v34, v35, vcc
	v_pk_mul_f32 v[32:33], v[32:33], v[34:35] op_sel_hi:[1,0]
	v_pk_mul_f32 v[36:37], v[30:31], v[34:35] op_sel_hi:[1,0]
	v_pk_mul_f32 v[28:29], v[28:29], v[34:35] op_sel_hi:[1,0]
	v_pk_mul_f32 v[30:31], v[26:27], v[34:35] op_sel_hi:[1,0]
	s_and_b64 vcc, exec, s[42:43]
	s_cbranch_vccnz .LBB0_751
	v_mul_f32_e32 v26, 0xbfb8aa3b, v36
	v_exp_f32_e32 v26, v26
	v_mul_f32_e32 v35, 0xbfb8aa3b, v37
	v_exp_f32_e32 v35, v35
	v_mul_f32_e32 v27, 0xbfb8aa3b, v30
	v_exp_f32_e32 v27, v27
	v_mul_f32_e32 v39, 0xbfb8aa3b, v31
	v_add_f32_e32 v26, 1.0, v26
	v_exp_f32_e32 v39, v39
	v_rcp_f32_e32 v26, v26
	v_add_f32_e32 v35, 1.0, v35
	v_rcp_f32_e32 v35, v35
	v_add_f32_e32 v27, 1.0, v27
	v_rcp_f32_e32 v27, v27
	v_add_f32_e32 v39, 1.0, v39
	v_mul_f32_e32 v26, 0x437f0000, v26
	v_rcp_f32_e32 v39, v39
	v_max_f32_e32 v26, 1.0, v26
	v_mul_f32_e32 v35, 0x437f0000, v35
	v_rndne_f32_e32 v26, v26
	v_max_f32_e32 v35, 1.0, v35
	v_cvt_pk_u8_f32 v26, v26, 0, 0
	v_mul_f32_e32 v27, 0x437f0000, v27
	v_rndne_f32_e32 v35, v35
	v_max_f32_e32 v27, 1.0, v27
	v_cvt_pk_u8_f32 v26, v35, 1, v26
	v_mul_f32_e32 v35, 0xbfb8aa3b, v32
	v_mul_f32_e32 v39, 0x437f0000, v39
	v_rndne_f32_e32 v27, v27
	v_exp_f32_e32 v35, v35
	v_max_f32_e32 v39, 1.0, v39
	v_cvt_pk_u8_f32 v27, v27, 0, 0
	v_rndne_f32_e32 v39, v39
	v_cvt_pk_u8_f32 v27, v39, 1, v27
	v_mul_f32_e32 v39, 0xbfb8aa3b, v28
	v_exp_f32_e32 v39, v39
	v_add_f32_e32 v35, 1.0, v35
	v_rcp_f32_e32 v35, v35
	v_mul_f32_e32 v40, 0xbfb8aa3b, v33
	v_add_f32_e32 v39, 1.0, v39
	v_rcp_f32_e32 v39, v39
	v_exp_f32_e32 v40, v40
	v_mul_f32_e32 v35, 0x437f0000, v35
	v_max_f32_e32 v35, 1.0, v35
	v_rndne_f32_e32 v35, v35
	v_cvt_pk_u8_f32 v26, v35, 2, v26
	v_mul_f32_e32 v35, 0x437f0000, v39
	v_add_f32_e32 v39, 1.0, v40
	v_mul_f32_e32 v40, 0xbfb8aa3b, v29
	v_rcp_f32_e32 v39, v39
	v_exp_f32_e32 v40, v40
	v_max_f32_e32 v35, 1.0, v35
	v_rndne_f32_e32 v35, v35
	v_cvt_pk_u8_f32 v27, v35, 2, v27
	v_mul_f32_e32 v35, 0x437f0000, v39
	v_add_f32_e32 v39, 1.0, v40
	v_rcp_f32_e32 v39, v39
	v_max_f32_e32 v35, 1.0, v35
	v_rndne_f32_e32 v35, v35
	v_cvt_pk_u8_f32 v26, v35, 3, v26
	v_mul_f32_e32 v35, 0x437f0000, v39
	v_max_f32_e32 v35, 1.0, v35
	v_mov_b64_e32 v[40:41], s[30:31]
	v_rndne_f32_e32 v35, v35
	v_mad_i64_i32 v[40:41], s[0:1], v38, s55, v[40:41]
	v_cvt_pk_u8_f32 v27, v35, 3, v27
	v_lshl_add_u64 v[40:41], v[40:41], 0, v[140:141]
	s_mov_b64 s[0:1], 0
	v_mov_b32_e32 v246, v26
	v_mov_b32_e32 v247, v27

.LBB0_753:
	v_mov_b32_e32 v35, v34
	v_mov_b32_e32 v28, v34
	v_mov_b32_e32 v29, v34
	v_pk_mul_f32 v[24:25], v[24:25], v[28:29]
	v_pk_mul_f32 v[22:23], v[22:23], v[34:35]
	v_pk_mul_f32 v[20:21], v[20:21], v[28:29]
	v_pk_mul_f32 v[18:19], v[18:19], v[34:35]
	s_and_b64 vcc, exec, s[42:43]
	s_mov_b64 s[0:1], -1
	s_cbranch_vccnz .LBB0_755
	v_mul_f32_e32 v28, 0xbfb8aa3b, v22
	v_exp_f32_e32 v28, v28
	v_mul_f32_e32 v30, 0xbfb8aa3b, v23
	v_exp_f32_e32 v30, v30
	v_mul_f32_e32 v29, 0xbfb8aa3b, v18
	v_exp_f32_e32 v29, v29
	v_mul_f32_e32 v31, 0xbfb8aa3b, v19
	v_add_f32_e32 v28, 1.0, v28
	v_exp_f32_e32 v31, v31
	v_rcp_f32_e32 v28, v28
	v_add_f32_e32 v30, 1.0, v30
	v_rcp_f32_e32 v30, v30
	v_add_f32_e32 v29, 1.0, v29
	v_rcp_f32_e32 v29, v29
	v_add_f32_e32 v31, 1.0, v31
	v_mul_f32_e32 v28, 0x437f0000, v28
	v_rcp_f32_e32 v31, v31
	v_max_f32_e32 v28, 1.0, v28
	v_mul_f32_e32 v30, 0x437f0000, v30
	v_rndne_f32_e32 v28, v28
	v_max_f32_e32 v30, 1.0, v30
	v_cvt_pk_u8_f32 v28, v28, 0, 0
	v_mul_f32_e32 v29, 0x437f0000, v29
	v_rndne_f32_e32 v30, v30
	v_max_f32_e32 v29, 1.0, v29
	v_cvt_pk_u8_f32 v28, v30, 1, v28
	v_mul_f32_e32 v30, 0xbfb8aa3b, v24
	v_mul_f32_e32 v31, 0x437f0000, v31
	v_rndne_f32_e32 v29, v29
	v_exp_f32_e32 v30, v30
	v_max_f32_e32 v31, 1.0, v31
	v_cvt_pk_u8_f32 v29, v29, 0, 0
	v_rndne_f32_e32 v31, v31
	v_cvt_pk_u8_f32 v29, v31, 1, v29
	v_mul_f32_e32 v31, 0xbfb8aa3b, v20
	v_exp_f32_e32 v31, v31
	v_add_f32_e32 v30, 1.0, v30
	v_rcp_f32_e32 v30, v30
	v_mul_f32_e32 v32, 0xbfb8aa3b, v25
	v_add_f32_e32 v31, 1.0, v31
	v_rcp_f32_e32 v31, v31
	v_exp_f32_e32 v32, v32
	v_mul_f32_e32 v30, 0x437f0000, v30
	v_max_f32_e32 v30, 1.0, v30
	v_rndne_f32_e32 v30, v30
	v_cvt_pk_u8_f32 v28, v30, 2, v28
	v_mul_f32_e32 v30, 0x437f0000, v31
	v_add_f32_e32 v31, 1.0, v32
	v_mul_f32_e32 v32, 0xbfb8aa3b, v21
	v_rcp_f32_e32 v31, v31
	v_exp_f32_e32 v32, v32
	v_max_f32_e32 v30, 1.0, v30
	v_rndne_f32_e32 v30, v30
	v_cvt_pk_u8_f32 v29, v30, 2, v29
	v_mul_f32_e32 v30, 0x437f0000, v31
	v_add_f32_e32 v31, 1.0, v32
	v_rcp_f32_e32 v31, v31
	v_max_f32_e32 v30, 1.0, v30
	v_rndne_f32_e32 v30, v30
	v_cvt_pk_u8_f32 v28, v30, 3, v28
	v_mul_f32_e32 v30, 0x437f0000, v31
	v_max_f32_e32 v30, 1.0, v30
	v_rndne_f32_e32 v30, v30
	v_cvt_pk_u8_f32 v29, v30, 3, v29
	v_mov_b64_e32 v[30:31], s[30:31]
	v_mad_i64_i32 v[30:31], s[0:1], v38, s55, v[30:31]
	v_lshl_add_u64 v[30:31], v[30:31], 0, v[140:141]
	s_mov_b64 s[0:1], 0
	v_mov_b32_e32 v244, v28
	v_mov_b32_e32 v245, v29
	v_mov_b32_e32 v250, v176
	v_mov_b32_e32 v251, 0
	v_lshl_add_u64 v[30:31], v[30:31], 0, v[250:251]
	global_store_dwordx4 v[30:31], v[244:247], off

.LBB0_757:
	v_ffbh_u32_e32 v18, v145
	v_min_u32_e32 v20, 32, v18
	v_lshlrev_b64 v[18:19], v20, v[144:145]
	v_min_u32_e32 v18, 1, v18
	v_or_b32_e32 v18, v19, v18
	v_cvt_f32_u32_e32 v18, v18
	v_sub_u32_e32 v19, 32, v20
	v_add_u32_e32 v22, 0xb0, v142
	s_mov_b64 s[0:1], -1
	v_ldexp_f32 v18, v18, v19
	v_mul_f32_e32 v18, 0x33800000, v18
	v_fmamk_f32 v18, v18, 0x3a800000, v210
	v_mul_f32_e32 v19, 0x4b800000, v18
	v_cmp_gt_f32_e32 vcc, s34, v18
	s_nop 1
	v_cndmask_b32_e32 v18, v18, v19, vcc
	v_rsq_f32_e32 v18, v18
	s_nop 0
	v_mul_f32_e32 v19, 0x45800000, v18
	v_cndmask_b32_e32 v18, v18, v19, vcc
	v_pk_mul_f32 v[16:17], v[16:17], v[18:19] op_sel_hi:[1,0]
	v_pk_mul_f32 v[20:21], v[14:15], v[18:19] op_sel_hi:[1,0]
	v_pk_mul_f32 v[12:13], v[12:13], v[18:19] op_sel_hi:[1,0]
	v_pk_mul_f32 v[14:15], v[10:11], v[18:19] op_sel_hi:[1,0]
	s_and_b64 vcc, exec, s[42:43]
	s_cbranch_vccnz .LBB0_759
	v_mul_f32_e32 v10, 0xbfb8aa3b, v20
	v_exp_f32_e32 v10, v10
	v_mul_f32_e32 v19, 0xbfb8aa3b, v21
	v_exp_f32_e32 v19, v19
	v_mul_f32_e32 v11, 0xbfb8aa3b, v14
	v_exp_f32_e32 v11, v11
	v_mul_f32_e32 v23, 0xbfb8aa3b, v15
	v_add_f32_e32 v10, 1.0, v10
	v_exp_f32_e32 v23, v23
	v_rcp_f32_e32 v10, v10
	v_add_f32_e32 v19, 1.0, v19
	v_rcp_f32_e32 v19, v19
	v_add_f32_e32 v11, 1.0, v11
	v_rcp_f32_e32 v11, v11
	v_add_f32_e32 v23, 1.0, v23
	v_mul_f32_e32 v10, 0x437f0000, v10
	v_rcp_f32_e32 v23, v23
	v_max_f32_e32 v10, 1.0, v10
	v_mul_f32_e32 v19, 0x437f0000, v19
	v_rndne_f32_e32 v10, v10
	v_max_f32_e32 v19, 1.0, v19
	v_cvt_pk_u8_f32 v10, v10, 0, 0
	v_mul_f32_e32 v11, 0x437f0000, v11
	v_rndne_f32_e32 v19, v19
	v_max_f32_e32 v11, 1.0, v11
	v_cvt_pk_u8_f32 v10, v19, 1, v10
	v_mul_f32_e32 v19, 0xbfb8aa3b, v16
	v_mul_f32_e32 v23, 0x437f0000, v23
	v_rndne_f32_e32 v11, v11
	v_exp_f32_e32 v19, v19
	v_max_f32_e32 v23, 1.0, v23
	v_cvt_pk_u8_f32 v11, v11, 0, 0
	v_rndne_f32_e32 v23, v23
	v_cvt_pk_u8_f32 v11, v23, 1, v11
	v_mul_f32_e32 v23, 0xbfb8aa3b, v12
	v_exp_f32_e32 v23, v23
	v_add_f32_e32 v19, 1.0, v19
	v_rcp_f32_e32 v19, v19
	v_mul_f32_e32 v24, 0xbfb8aa3b, v17
	v_add_f32_e32 v23, 1.0, v23
	v_rcp_f32_e32 v23, v23
	v_exp_f32_e32 v24, v24
	v_mul_f32_e32 v19, 0x437f0000, v19
	v_max_f32_e32 v19, 1.0, v19
	v_rndne_f32_e32 v19, v19
	v_cvt_pk_u8_f32 v10, v19, 2, v10
	v_mul_f32_e32 v19, 0x437f0000, v23
	v_add_f32_e32 v23, 1.0, v24
	v_mul_f32_e32 v24, 0xbfb8aa3b, v13
	v_rcp_f32_e32 v23, v23
	v_exp_f32_e32 v24, v24
	v_max_f32_e32 v19, 1.0, v19
	v_rndne_f32_e32 v19, v19
	v_cvt_pk_u8_f32 v11, v19, 2, v11
	v_mul_f32_e32 v19, 0x437f0000, v23
	v_add_f32_e32 v23, 1.0, v24
	v_rcp_f32_e32 v23, v23
	v_max_f32_e32 v19, 1.0, v19
	v_rndne_f32_e32 v19, v19
	v_cvt_pk_u8_f32 v10, v19, 3, v10
	v_mul_f32_e32 v19, 0x437f0000, v23
	v_max_f32_e32 v19, 1.0, v19
	v_mov_b64_e32 v[24:25], s[30:31]
	v_rndne_f32_e32 v19, v19
	v_mad_i64_i32 v[24:25], s[0:1], v22, s55, v[24:25]
	v_cvt_pk_u8_f32 v11, v19, 3, v11
	v_lshl_add_u64 v[24:25], v[24:25], 0, v[140:141]
	s_mov_b64 s[0:1], 0
	v_mov_b32_e32 v246, v10
	v_mov_b32_e32 v247, v11

.LBB0_761:
	v_mov_b32_e32 v19, v18
	v_mov_b32_e32 v12, v18
	v_mov_b32_e32 v13, v18
	v_pk_mul_f32 v[8:9], v[8:9], v[12:13]
	v_pk_mul_f32 v[6:7], v[6:7], v[18:19]
	v_pk_mul_f32 v[4:5], v[4:5], v[12:13]
	v_pk_mul_f32 v[2:3], v[2:3], v[18:19]
	s_and_b64 vcc, exec, s[42:43]
	s_mov_b64 s[0:1], -1
	s_cbranch_vccnz .LBB0_764
	v_mul_f32_e32 v12, 0xbfb8aa3b, v6
	v_exp_f32_e32 v12, v12
	v_mul_f32_e32 v14, 0xbfb8aa3b, v7
	v_exp_f32_e32 v14, v14
	v_mul_f32_e32 v13, 0xbfb8aa3b, v2
	v_exp_f32_e32 v13, v13
	v_mul_f32_e32 v15, 0xbfb8aa3b, v3
	v_add_f32_e32 v12, 1.0, v12
	v_exp_f32_e32 v15, v15
	v_rcp_f32_e32 v12, v12
	v_add_f32_e32 v14, 1.0, v14
	v_rcp_f32_e32 v14, v14
	v_add_f32_e32 v13, 1.0, v13
	v_rcp_f32_e32 v13, v13
	v_add_f32_e32 v15, 1.0, v15
	v_mul_f32_e32 v12, 0x437f0000, v12
	v_rcp_f32_e32 v15, v15
	v_max_f32_e32 v12, 1.0, v12
	v_mul_f32_e32 v14, 0x437f0000, v14
	v_rndne_f32_e32 v12, v12
	v_max_f32_e32 v14, 1.0, v14
	v_cvt_pk_u8_f32 v12, v12, 0, 0
	v_mul_f32_e32 v13, 0x437f0000, v13
	v_rndne_f32_e32 v14, v14
	v_max_f32_e32 v13, 1.0, v13
	v_cvt_pk_u8_f32 v12, v14, 1, v12
	v_mul_f32_e32 v14, 0xbfb8aa3b, v8
	v_mul_f32_e32 v15, 0x437f0000, v15
	v_rndne_f32_e32 v13, v13
	v_exp_f32_e32 v14, v14
	v_max_f32_e32 v15, 1.0, v15
	v_cvt_pk_u8_f32 v13, v13, 0, 0
	v_rndne_f32_e32 v15, v15
	v_cvt_pk_u8_f32 v13, v15, 1, v13
	v_mul_f32_e32 v15, 0xbfb8aa3b, v4
	v_exp_f32_e32 v15, v15
	v_add_f32_e32 v14, 1.0, v14
	v_rcp_f32_e32 v14, v14
	v_mul_f32_e32 v16, 0xbfb8aa3b, v9
	v_add_f32_e32 v15, 1.0, v15
	v_rcp_f32_e32 v15, v15
	v_exp_f32_e32 v16, v16
	v_mul_f32_e32 v14, 0x437f0000, v14
	v_max_f32_e32 v14, 1.0, v14
	v_rndne_f32_e32 v14, v14
	v_cvt_pk_u8_f32 v12, v14, 2, v12
	v_mul_f32_e32 v14, 0x437f0000, v15
	v_add_f32_e32 v15, 1.0, v16
	v_mul_f32_e32 v16, 0xbfb8aa3b, v5
	v_rcp_f32_e32 v15, v15
	v_exp_f32_e32 v16, v16
	v_max_f32_e32 v14, 1.0, v14
	v_rndne_f32_e32 v14, v14
	v_cvt_pk_u8_f32 v13, v14, 2, v13
	v_mul_f32_e32 v14, 0x437f0000, v15
	v_add_f32_e32 v15, 1.0, v16
	v_rcp_f32_e32 v15, v15
	v_max_f32_e32 v14, 1.0, v14
	v_rndne_f32_e32 v14, v14
	v_cvt_pk_u8_f32 v12, v14, 3, v12
	v_mul_f32_e32 v14, 0x437f0000, v15
	v_max_f32_e32 v14, 1.0, v14
	v_rndne_f32_e32 v14, v14
	v_cvt_pk_u8_f32 v13, v14, 3, v13
	v_mov_b64_e32 v[14:15], s[30:31]
	v_mad_i64_i32 v[14:15], s[0:1], v22, s55, v[14:15]
	v_lshl_add_u64 v[14:15], v[14:15], 0, v[140:141]
	v_mov_b32_e32 v244, v12
	v_mov_b32_e32 v245, v13
	v_mov_b32_e32 v250, v176
	v_mov_b32_e32 v251, 0
	v_lshl_add_u64 v[14:15], v[14:15], 0, v[250:251]
	global_store_dwordx4 v[14:15], v[244:247], off
	s_cbranch_execz .LBB0_765
